# peel_p2+attention finalize stores widened via LDS transpose
# speedup vs baseline: 1.0101x; 1.0101x over previous
; #define PG8_STAGE(bufoff, gbase, voff) do { _Pragma("unroll") for (int _i = 0; _i < 2; ++_i) \
;         __builtin_amdgcn_global_load_lds((const unsigned*)((const char*)(gbase) + (voff)[_i]), (PG8_LAS unsigned*)(lds + (bufoff) + ldsw + _i * 8192), 16, 0, 0); } while (0)
; #define PG8_LDA(dst, b, h) do { _Pragma("unroll") for (int m = 0; m < 4; ++m) _Pragma("unroll") for (int k = 0; k < 2; ++k) dst[m][k] = *(const PG8_LAS bf16x8*)(lds + PG8_SA(b, h) + aoff + m * 2048 + k * 1024); } while (0)
; #define PG8_LDB(dst, b, h) do { _Pragma("unroll") for (int n = 0; n < 2; ++n) _Pragma("unroll") for (int k = 0; k < 2; ++k) dst[n][k] = *(const PG8_LAS bf16x8*)(lds + PG8_SB(b, h) + boff + n * 2048 + k * 1024); } while (0)
; #define PG8_WAIT_V(n) asm volatile("s_waitcnt vmcnt(" #n ")" ::: "memory")
; #define PG8_WAIT_L(n) asm volatile("s_waitcnt lgkmcnt(" #n ")" ::: "memory")
; #define PG8_BAR __builtin_amdgcn_s_barrier()
; #define PG8_SCHED __builtin_amdgcn_sched_barrier(0)
; template <class Epi, class Sched, bool ALIGN_EPI = false, bool SP2 = false>
; __device__ __forceinline__ void gemm_phase(PG8_LAS unsigned char* lds, const Gemm g, const Sched& S, const Epi& E) {
;     ...
;         const char* nA = has_next ? (const char*)g.A + (size_t)nxt.pm * tstepA + (size_t)nxt.pn * apn : cA; const char* nB = has_next ? (const char*)g.Bt + (size_t)nxt.pn * tstepB : cB;
;         for (int t = 0; t < nt; t += 2) {
;             const bool last = (t == nt - 2);
;             const char* a1 = cA + (size_t)(t + 1) * kstep;
;             const char* a2 = last ? nA : cA + (size_t)(t + 2) * kstep; const char* b2 = last ? nB : cB + (size_t)(t + 2) * kstep;
;             const char* a3 = a2 + kstep; const char* b3 = b2 + kstep;
;             if (last && has_next) S.a_ready(nxt);
;             if constexpr (SP2) {
;             PG8_LDB(B0, 0, 0); PG8_LDB(B1, 0, 1); PG8_SCHED; PG8_LDA(At, 0, 0); PG8_STAGE(PG8_SA(1, 1), a1 + hstepA, voffA);
;             PG8_WAIT_V(8); PG8_WAIT_L(0); PG8_BAR; PG8_MMA(0, 0, At, B0); PG8_MMA(0, 1, At, B1); PG8_BAR; PG8_SCHED;
;     ...
;         for (int a = 0; a < 2; ++a)
; #pragma unroll
;             for (int b = 0; b < 2; ++b)
; #pragma unroll
;                 for (int m = 0; m < 4; ++m)
; #pragma unroll
;                     for (int n = 0; n < 2; ++n) acc[a][b][m][n] = (f32x4){0.f, 0.f, 0.f, 0.f};
.LBB0_196:
	s_ashr_i32 s15, s14, 31
	s_lshl_b64 s[16:17], s[14:15], 19
	s_add_u32 s16, s24, s16
	s_addc_u32 s17, s25, s17
	s_and_b64 s[56:57], s[4:5], exec
	s_cselect_b32 s15, s17, s61
	s_cselect_b32 vcc_lo, s16, s60
	s_ashr_i32 s13, s12, 31
	s_lshl_b64 s[56:57], s[12:13], 19
	s_add_u32 s56, s82, s56
	s_addc_u32 s57, s83, s57
	s_and_b64 s[74:75], s[4:5], exec
	s_cselect_b32 s13, s57, s67
	s_cselect_b32 vcc_hi, s56, s66
	s_add_u32 s60, s60, 0x40080
	s_addc_u32 s61, s61, 0
	s_add_u32 s80, s66, 0x100
	v_mov_b32_e32 v0, 0
	s_addc_u32 s81, s67, 0
	s_mov_b32 s74, -2
	s_cmp_lg_u32 s90, 1
	s_cbranch_scc1 .Lpeel_p2
	v_mov_b32_e32 v1, v0
	v_mov_b32_e32 v2, v0
	v_mov_b32_e32 v3, v0
	v_mov_b32_e32 v4, v0
	v_mov_b32_e32 v5, v0
	v_mov_b32_e32 v6, v0
	v_mov_b32_e32 v7, v0
	v_mov_b32_e32 v8, v0
	v_mov_b32_e32 v9, v0
	v_mov_b32_e32 v10, v0
	v_mov_b32_e32 v11, v0
	v_mov_b32_e32 v12, v0
	v_mov_b32_e32 v13, v0
	v_mov_b32_e32 v14, v0
	v_mov_b32_e32 v15, v0
	v_mov_b32_e32 v16, v0
	v_mov_b32_e32 v17, v0
	v_mov_b32_e32 v18, v0
	v_mov_b32_e32 v19, v0
	v_mov_b32_e32 v20, v0
	v_mov_b32_e32 v21, v0
	v_mov_b32_e32 v22, v0
	v_mov_b32_e32 v23, v0
	v_mov_b32_e32 v24, v0
	v_mov_b32_e32 v25, v0
	v_mov_b32_e32 v26, v0
	v_mov_b32_e32 v27, v0
	v_mov_b32_e32 v28, v0
	v_mov_b32_e32 v29, v0
	v_mov_b32_e32 v30, v0
	v_mov_b32_e32 v31, v0
	v_mov_b32_e32 v52, v0
	v_mov_b32_e32 v53, v0
	v_mov_b32_e32 v54, v0
	v_mov_b32_e32 v55, v0
	v_mov_b32_e32 v60, v0
	v_mov_b32_e32 v61, v0
	v_mov_b32_e32 v62, v0
	v_mov_b32_e32 v63, v0
	v_mov_b32_e32 v72, v0
	v_mov_b32_e32 v73, v0
	v_mov_b32_e32 v74, v0
	v_mov_b32_e32 v75, v0
	v_mov_b32_e32 v76, v0
	v_mov_b32_e32 v77, v0
	v_mov_b32_e32 v78, v0
	v_mov_b32_e32 v79, v0
	v_mov_b32_e32 v80, v0
	v_mov_b32_e32 v81, v0
	v_mov_b32_e32 v82, v0
	v_mov_b32_e32 v83, v0
	v_mov_b32_e32 v84, v0
	v_mov_b32_e32 v85, v0
	v_mov_b32_e32 v86, v0
	v_mov_b32_e32 v87, v0
	v_mov_b32_e32 v88, v0
	v_mov_b32_e32 v89, v0
	v_mov_b32_e32 v90, v0
	v_mov_b32_e32 v91, v0
	v_mov_b32_e32 v92, v0
	v_mov_b32_e32 v93, v0
	v_mov_b32_e32 v94, v0
	v_mov_b32_e32 v95, v0
	v_mov_b32_e32 v32, v0
	v_mov_b32_e32 v33, v0
	v_mov_b32_e32 v34, v0
	v_mov_b32_e32 v35, v0
	v_mov_b32_e32 v36, v0
	v_mov_b32_e32 v37, v0
	v_mov_b32_e32 v38, v0
	v_mov_b32_e32 v39, v0
	v_mov_b32_e32 v40, v0
	v_mov_b32_e32 v41, v0
	v_mov_b32_e32 v42, v0
	v_mov_b32_e32 v43, v0
	v_mov_b32_e32 v44, v0
	v_mov_b32_e32 v45, v0
	v_mov_b32_e32 v46, v0
	v_mov_b32_e32 v47, v0
	v_mov_b32_e32 v48, v0
	v_mov_b32_e32 v49, v0
	v_mov_b32_e32 v50, v0
	v_mov_b32_e32 v51, v0
	v_mov_b32_e32 v56, v0
	v_mov_b32_e32 v57, v0
	v_mov_b32_e32 v58, v0
	v_mov_b32_e32 v59, v0
	v_mov_b32_e32 v64, v0
	v_mov_b32_e32 v65, v0
	v_mov_b32_e32 v66, v0
	v_mov_b32_e32 v67, v0
	v_mov_b32_e32 v68, v0
	v_mov_b32_e32 v69, v0
	v_mov_b32_e32 v70, v0
	v_mov_b32_e32 v71, v0
	v_mov_b32_e32 v96, v0
	v_mov_b32_e32 v97, v0
	v_mov_b32_e32 v98, v0
	v_mov_b32_e32 v99, v0
	v_mov_b32_e32 v100, v0
	v_mov_b32_e32 v101, v0
	v_mov_b32_e32 v102, v0
	v_mov_b32_e32 v103, v0
	v_mov_b32_e32 v104, v0
	v_mov_b32_e32 v105, v0
	v_mov_b32_e32 v106, v0
	v_mov_b32_e32 v107, v0
	v_mov_b32_e32 v108, v0
	v_mov_b32_e32 v109, v0
	v_mov_b32_e32 v110, v0
	v_mov_b32_e32 v111, v0
	v_mov_b32_e32 v112, v0
	v_mov_b32_e32 v113, v0
	v_mov_b32_e32 v114, v0
	v_mov_b32_e32 v115, v0
	v_mov_b32_e32 v116, v0
	v_mov_b32_e32 v117, v0
	v_mov_b32_e32 v118, v0
	v_mov_b32_e32 v119, v0
	v_mov_b32_e32 v120, v0
	v_mov_b32_e32 v121, v0
	v_mov_b32_e32 v122, v0
	v_mov_b32_e32 v123, v0
	v_mov_b32_e32 v124, v0
	v_mov_b32_e32 v125, v0
	v_mov_b32_e32 v126, v0
	v_mov_b32_e32 v127, v0
.LBB0_197:
	s_waitcnt lgkmcnt(0)
	ds_read_b128 v[146:149], v159
	ds_read_b128 v[162:165], v159 offset:1024
	ds_read_b128 v[166:169], v159 offset:2048
	ds_read_b128 v[170:173], v159 offset:3072
	ds_read_b128 v[176:179], v160
	ds_read_b128 v[180:183], v160 offset:1024
	ds_read_b128 v[184:187], v160 offset:2048
	ds_read_b128 v[188:191], v160 offset:3072
	s_add_u32 s66, s60, 0xfffc0080
	s_addc_u32 s67, s61, -1
	s_cmp_eq_u32 s74, 12
	s_cselect_b32 s85, s15, s67
	s_cselect_b32 s84, vcc_lo, s66
	s_cselect_b32 s67, s13, s81
	s_cselect_b32 s66, vcc_hi, s80
	v_lshl_add_u64 v[224:225], s[60:61], 0, v[138:139]
	s_add_i32 m0, s59, 0xc000
	ds_read_b128 v[192:195], v161
	ds_read_b128 v[196:199], v161 offset:1024
	ds_read_b128 v[200:203], v161 offset:2048
	ds_read_b128 v[204:207], v161 offset:3072
	ds_read_b128 v[208:211], v161 offset:4096
	ds_read_b128 v[212:215], v161 offset:5120
	ds_read_b128 v[216:219], v161 offset:6144
	ds_read_b128 v[220:223], v161 offset:7168
	global_load_lds_dwordx4 v[224:225], off
	v_lshl_add_u64 v[224:225], s[60:61], 0, v[140:141]
	s_add_i32 m0, s59, 0xe000
	s_nop 0
	global_load_lds_dwordx4 v[224:225], off
	s_waitcnt vmcnt(8)
	s_waitcnt lgkmcnt(0)
	s_barrier
; #define PG8_STAGE(bufoff, gbase, voff) do { _Pragma("unroll") for (int _i = 0; _i < 2; ++_i) \
;         __builtin_amdgcn_global_load_lds((const unsigned*)((const char*)(gbase) + (voff)[_i]), (PG8_LAS unsigned*)(lds + (bufoff) + ldsw + _i * 8192), 16, 0, 0); } while (0)
; #define PG8_LDA(dst, b, h) do { _Pragma("unroll") for (int m = 0; m < 4; ++m) _Pragma("unroll") for (int k = 0; k < 2; ++k) dst[m][k] = *(const PG8_LAS bf16x8*)(lds + PG8_SA(b, h) + aoff + m * 2048 + k * 1024); } while (0)
; #define PG8_MMA(ai, bj, At, Bt) do { __builtin_amdgcn_s_setprio(1); _Pragma("unroll") for (int m = 0; m < 4; ++m) _Pragma("unroll") for (int n = 0; n < 2; ++n) _Pragma("unroll") for (int k = 0; k < 2; ++k) \
;         acc[ai][bj][m][n] = __builtin_amdgcn_mfma_f32_16x16x32_bf16(Bt[n][k], At[m][k], acc[ai][bj][m][n], 0, 0, 0); __builtin_amdgcn_s_setprio(0); } while (0)
; #define PG8_WAIT_V(n) asm volatile("s_waitcnt vmcnt(" #n ")" ::: "memory")
; #define PG8_WAIT_L(n) asm volatile("s_waitcnt lgkmcnt(" #n ")" ::: "memory")
; #define PG8_BAR __builtin_amdgcn_s_barrier()
; #define PG8_SCHED __builtin_amdgcn_sched_barrier(0)
; template <class Epi, class Sched, bool ALIGN_EPI = false, bool SP2 = false>
; __device__ __forceinline__ void gemm_phase(PG8_LAS unsigned char* lds, const Gemm g, const Sched& S, const Epi& E) {
;     ...
;             PG8_WAIT_V(8); PG8_WAIT_L(0); PG8_BAR; PG8_MMA(0, 0, At, B0); PG8_MMA(0, 1, At, B1); PG8_BAR; PG8_SCHED;
;             PG8_LDA(At, 0, 1); PG8_STAGE(PG8_SB(0, 0), b2, voffB); PG8_STAGE(PG8_SB(0, 1), b2 + hstepB, voffB); PG8_STAGE(PG8_SA(0, 0), a2, voffA);
;             PG8_WAIT_V(8); PG8_WAIT_L(0); PG8_BAR; PG8_MMA(1, 0, At, B0); PG8_MMA(1, 1, At, B1); PG8_BAR; PG8_SCHED;
	s_setprio 1
	s_waitcnt lgkmcnt(0)
	v_mfma_f32_16x16x32_bf16 v[124:127], v[146:149], v[192:195], v[124:127]
	v_mfma_f32_16x16x32_bf16 v[120:123], v[166:169], v[192:195], v[120:123]
	v_mfma_f32_16x16x32_bf16 v[116:119], v[146:149], v[200:203], v[116:119]
	v_mfma_f32_16x16x32_bf16 v[112:115], v[166:169], v[200:203], v[112:115]
	v_mfma_f32_16x16x32_bf16 v[108:111], v[146:149], v[208:211], v[108:111]
	v_mfma_f32_16x16x32_bf16 v[104:107], v[166:169], v[208:211], v[104:107]
	v_mfma_f32_16x16x32_bf16 v[100:103], v[146:149], v[216:219], v[100:103]
	v_mfma_f32_16x16x32_bf16 v[96:99], v[166:169], v[216:219], v[96:99]
	v_mfma_f32_16x16x32_bf16 v[124:127], v[162:165], v[196:199], v[124:127]
	v_mfma_f32_16x16x32_bf16 v[120:123], v[170:173], v[196:199], v[120:123]
	v_mfma_f32_16x16x32_bf16 v[116:119], v[162:165], v[204:207], v[116:119]
	v_mfma_f32_16x16x32_bf16 v[112:115], v[170:173], v[204:207], v[112:115]
	v_mfma_f32_16x16x32_bf16 v[108:111], v[162:165], v[212:215], v[108:111]
	v_mfma_f32_16x16x32_bf16 v[104:107], v[170:173], v[212:215], v[104:107]
	v_mfma_f32_16x16x32_bf16 v[100:103], v[162:165], v[220:223], v[100:103]
	v_mfma_f32_16x16x32_bf16 v[96:99], v[170:173], v[220:223], v[96:99]
	s_setprio 0
	s_setprio 1
	v_mfma_f32_16x16x32_bf16 v[68:71], v[176:179], v[192:195], v[68:71]
	v_mfma_f32_16x16x32_bf16 v[64:67], v[184:187], v[192:195], v[64:67]
	v_mfma_f32_16x16x32_bf16 v[56:59], v[176:179], v[200:203], v[56:59]
	v_mfma_f32_16x16x32_bf16 v[48:51], v[184:187], v[200:203], v[48:51]
	v_mfma_f32_16x16x32_bf16 v[44:47], v[176:179], v[208:211], v[44:47]
	v_mfma_f32_16x16x32_bf16 v[40:43], v[184:187], v[208:211], v[40:43]
	v_mfma_f32_16x16x32_bf16 v[36:39], v[176:179], v[216:219], v[36:39]
	v_mfma_f32_16x16x32_bf16 v[32:35], v[184:187], v[216:219], v[32:35]
	v_mfma_f32_16x16x32_bf16 v[68:71], v[180:183], v[196:199], v[68:71]
	v_mfma_f32_16x16x32_bf16 v[64:67], v[188:191], v[196:199], v[64:67]
	v_mfma_f32_16x16x32_bf16 v[56:59], v[180:183], v[204:207], v[56:59]
	v_mfma_f32_16x16x32_bf16 v[48:51], v[188:191], v[204:207], v[48:51]
	v_mfma_f32_16x16x32_bf16 v[44:47], v[180:183], v[212:215], v[44:47]
	v_mfma_f32_16x16x32_bf16 v[40:43], v[188:191], v[212:215], v[40:43]
	v_mfma_f32_16x16x32_bf16 v[36:39], v[180:183], v[220:223], v[36:39]
	v_mfma_f32_16x16x32_bf16 v[32:35], v[188:191], v[220:223], v[32:35]
	s_setprio 0
	s_barrier
	s_add_i32 s75, s38, s27
	v_lshl_add_u64 v[224:225], s[66:67], 0, v[132:133]
	s_mov_b32 m0, s75
	ds_read_b128 v[192:195], v161 offset:16384
	ds_read_b128 v[196:199], v161 offset:17408
	ds_read_b128 v[200:203], v161 offset:18432
	ds_read_b128 v[204:207], v161 offset:19456
	ds_read_b128 v[208:211], v161 offset:20480
	ds_read_b128 v[212:215], v161 offset:21504
	ds_read_b128 v[216:219], v161 offset:22528
	ds_read_b128 v[220:223], v161 offset:23552
	global_load_lds_dwordx4 v[224:225], off
	s_add_i32 m0, s75, 0x2000
	s_add_u32 s76, s66, 0x40000
	v_lshl_add_u64 v[226:227], s[66:67], 0, v[128:129]
	s_addc_u32 s77, s67, 0
	s_add_i32 s75, s39, s27
	global_load_lds_dwordx4 v[226:227], off
	v_lshl_add_u64 v[228:229], s[76:77], 0, v[132:133]
	s_mov_b32 m0, s75
	v_lshl_add_u64 v[230:231], s[84:85], 0, v[130:131]
	global_load_lds_dwordx4 v[228:229], off
	v_lshl_add_u64 v[228:229], s[76:77], 0, v[128:129]
	s_add_i32 m0, s75, 0x2000
	s_nop 0
	global_load_lds_dwordx4 v[228:229], off
	v_lshl_add_u64 v[228:229], s[84:85], 0, v[134:135]
	s_mov_b32 m0, s59
	s_nop 0
	global_load_lds_dwordx4 v[228:229], off
	s_mov_b32 m0, s86
	s_nop 0
	global_load_lds_dwordx4 v[230:231], off
	s_waitcnt vmcnt(8)
	s_waitcnt lgkmcnt(0)
	s_barrier
	s_setprio 1
	s_waitcnt lgkmcnt(0)
	v_mfma_f32_16x16x32_bf16 v[92:95], v[146:149], v[192:195], v[92:95]
	v_mfma_f32_16x16x32_bf16 v[88:91], v[166:169], v[192:195], v[88:91]
	v_mfma_f32_16x16x32_bf16 v[84:87], v[146:149], v[200:203], v[84:87]
	v_mfma_f32_16x16x32_bf16 v[80:83], v[166:169], v[200:203], v[80:83]
	v_mfma_f32_16x16x32_bf16 v[76:79], v[146:149], v[208:211], v[76:79]
	v_mfma_f32_16x16x32_bf16 v[72:75], v[166:169], v[208:211], v[72:75]
	v_mfma_f32_16x16x32_bf16 v[60:63], v[146:149], v[216:219], v[60:63]
	v_mfma_f32_16x16x32_bf16 v[52:55], v[166:169], v[216:219], v[52:55]
	v_mfma_f32_16x16x32_bf16 v[92:95], v[162:165], v[196:199], v[92:95]
	v_mfma_f32_16x16x32_bf16 v[88:91], v[170:173], v[196:199], v[88:91]
	v_mfma_f32_16x16x32_bf16 v[84:87], v[162:165], v[204:207], v[84:87]
	v_mfma_f32_16x16x32_bf16 v[80:83], v[170:173], v[204:207], v[80:83]
	v_mfma_f32_16x16x32_bf16 v[76:79], v[162:165], v[212:215], v[76:79]
	v_mfma_f32_16x16x32_bf16 v[72:75], v[170:173], v[212:215], v[72:75]
	v_mfma_f32_16x16x32_bf16 v[60:63], v[162:165], v[220:223], v[60:63]
	v_mfma_f32_16x16x32_bf16 v[52:55], v[170:173], v[220:223], v[52:55]
	s_setprio 0
	s_setprio 1
	v_mfma_f32_16x16x32_bf16 v[28:31], v[176:179], v[192:195], v[28:31]
	v_mfma_f32_16x16x32_bf16 v[24:27], v[184:187], v[192:195], v[24:27]
	v_mfma_f32_16x16x32_bf16 v[20:23], v[176:179], v[200:203], v[20:23]
	v_mfma_f32_16x16x32_bf16 v[16:19], v[184:187], v[200:203], v[16:19]
	v_mfma_f32_16x16x32_bf16 v[12:15], v[176:179], v[208:211], v[12:15]
	v_mfma_f32_16x16x32_bf16 v[8:11], v[184:187], v[208:211], v[8:11]
	v_mfma_f32_16x16x32_bf16 v[4:7], v[176:179], v[216:219], v[4:7]
	v_mfma_f32_16x16x32_bf16 v[0:3], v[184:187], v[216:219], v[0:3]
	v_mfma_f32_16x16x32_bf16 v[28:31], v[180:183], v[196:199], v[28:31]
	v_mfma_f32_16x16x32_bf16 v[24:27], v[188:191], v[196:199], v[24:27]
	v_mfma_f32_16x16x32_bf16 v[20:23], v[180:183], v[204:207], v[20:23]
	v_mfma_f32_16x16x32_bf16 v[16:19], v[188:191], v[204:207], v[16:19]
	v_mfma_f32_16x16x32_bf16 v[12:15], v[180:183], v[212:215], v[12:15]
	v_mfma_f32_16x16x32_bf16 v[8:11], v[188:191], v[212:215], v[8:11]
	v_mfma_f32_16x16x32_bf16 v[4:7], v[180:183], v[220:223], v[4:7]
	v_mfma_f32_16x16x32_bf16 v[0:3], v[188:191], v[220:223], v[0:3]
	s_setprio 0
	s_barrier
; #define PG8_STAGE(bufoff, gbase, voff) do { _Pragma("unroll") for (int _i = 0; _i < 2; ++_i) \
;         __builtin_amdgcn_global_load_lds((const unsigned*)((const char*)(gbase) + (voff)[_i]), (PG8_LAS unsigned*)(lds + (bufoff) + ldsw + _i * 8192), 16, 0, 0); } while (0)
; #define PG8_LDA(dst, b, h) do { _Pragma("unroll") for (int m = 0; m < 4; ++m) _Pragma("unroll") for (int k = 0; k < 2; ++k) dst[m][k] = *(const PG8_LAS bf16x8*)(lds + PG8_SA(b, h) + aoff + m * 2048 + k * 1024); } while (0)
; #define PG8_LDB(dst, b, h) do { _Pragma("unroll") for (int n = 0; n < 2; ++n) _Pragma("unroll") for (int k = 0; k < 2; ++k) dst[n][k] = *(const PG8_LAS bf16x8*)(lds + PG8_SB(b, h) + boff + n * 2048 + k * 1024); } while (0)
; #define PG8_MMA(ai, bj, At, Bt) do { __builtin_amdgcn_s_setprio(1); _Pragma("unroll") for (int m = 0; m < 4; ++m) _Pragma("unroll") for (int n = 0; n < 2; ++n) _Pragma("unroll") for (int k = 0; k < 2; ++k) \
;         acc[ai][bj][m][n] = __builtin_amdgcn_mfma_f32_16x16x32_bf16(Bt[n][k], At[m][k], acc[ai][bj][m][n], 0, 0, 0); __builtin_amdgcn_s_setprio(0); } while (0)
; #define PG8_WAIT_V(n) asm volatile("s_waitcnt vmcnt(" #n ")" ::: "memory")
; #define PG8_WAIT_L(n) asm volatile("s_waitcnt lgkmcnt(" #n ")" ::: "memory")
; #define PG8_BAR __builtin_amdgcn_s_barrier()
; #define PG8_SCHED __builtin_amdgcn_sched_barrier(0)
; template <class Epi, class Sched, bool ALIGN_EPI = false, bool SP2 = false>
; __device__ __forceinline__ void gemm_phase(PG8_LAS unsigned char* lds, const Gemm g, const Sched& S, const Epi& E) {
;     ...
;             PG8_LDB(B0, 1, 0); PG8_LDB(B1, 1, 1); PG8_SCHED; PG8_LDA(At, 1, 0); PG8_STAGE(PG8_SA(0, 1), a2 + hstepA, voffA);
;             PG8_WAIT_V(8); PG8_WAIT_L(0); PG8_BAR; PG8_MMA(0, 0, At, B0); PG8_MMA(0, 1, At, B1); PG8_BAR; PG8_SCHED;
	s_add_i32 s75, 0, 0x18000
	s_add_i32 s33, 0, 0x1c000
	v_add_u32_e32 v170, s75, v151
	v_add_u32_e32 v175, s33, v151
	ds_read_b128 v[146:149], v170
	ds_read_b128 v[162:165], v170 offset:1024
	ds_read_b128 v[166:169], v170 offset:2048
	ds_read_b128 v[170:173], v170 offset:3072
	ds_read_b128 v[176:179], v175
	ds_read_b128 v[180:183], v175 offset:1024
	ds_read_b128 v[184:187], v175 offset:2048
	ds_read_b128 v[188:191], v175 offset:3072
	s_add_u32 s76, s84, 0x40000
	s_addc_u32 s77, s85, 0
	s_mov_b32 m0, s87
	v_lshl_add_u64 v[232:233], s[76:77], 0, v[134:135]
	ds_read_b128 v[192:195], v161 offset:32768
	ds_read_b128 v[196:199], v161 offset:33792
	ds_read_b128 v[200:203], v161 offset:34816
	ds_read_b128 v[204:207], v161 offset:35840
	ds_read_b128 v[208:211], v161 offset:36864
	ds_read_b128 v[212:215], v161 offset:37888
	ds_read_b128 v[216:219], v161 offset:38912
	ds_read_b128 v[220:223], v161 offset:39936
	global_load_lds_dwordx4 v[232:233], off
	v_lshl_add_u64 v[232:233], s[76:77], 0, v[130:131]
	s_mov_b32 m0, s88
	s_nop 0
	global_load_lds_dwordx4 v[232:233], off
	s_waitcnt vmcnt(8)
	s_waitcnt lgkmcnt(0)
	s_barrier
	s_setprio 1
	s_waitcnt lgkmcnt(0)
	v_mfma_f32_16x16x32_bf16 v[124:127], v[146:149], v[192:195], v[124:127]
	v_mfma_f32_16x16x32_bf16 v[120:123], v[166:169], v[192:195], v[120:123]
	v_mfma_f32_16x16x32_bf16 v[116:119], v[146:149], v[200:203], v[116:119]
	v_mfma_f32_16x16x32_bf16 v[112:115], v[166:169], v[200:203], v[112:115]
	v_mfma_f32_16x16x32_bf16 v[108:111], v[146:149], v[208:211], v[108:111]
	v_mfma_f32_16x16x32_bf16 v[104:107], v[166:169], v[208:211], v[104:107]
	v_mfma_f32_16x16x32_bf16 v[100:103], v[146:149], v[216:219], v[100:103]
	v_mfma_f32_16x16x32_bf16 v[96:99], v[166:169], v[216:219], v[96:99]
	v_mfma_f32_16x16x32_bf16 v[124:127], v[162:165], v[196:199], v[124:127]
	v_mfma_f32_16x16x32_bf16 v[120:123], v[170:173], v[196:199], v[120:123]
	v_mfma_f32_16x16x32_bf16 v[116:119], v[162:165], v[204:207], v[116:119]
	v_mfma_f32_16x16x32_bf16 v[112:115], v[170:173], v[204:207], v[112:115]
	v_mfma_f32_16x16x32_bf16 v[108:111], v[162:165], v[212:215], v[108:111]
	v_mfma_f32_16x16x32_bf16 v[104:107], v[170:173], v[212:215], v[104:107]
	v_mfma_f32_16x16x32_bf16 v[100:103], v[162:165], v[220:223], v[100:103]
	v_mfma_f32_16x16x32_bf16 v[96:99], v[170:173], v[220:223], v[96:99]
	s_setprio 0
	s_setprio 1
	v_mfma_f32_16x16x32_bf16 v[68:71], v[176:179], v[192:195], v[68:71]
	v_mfma_f32_16x16x32_bf16 v[64:67], v[184:187], v[192:195], v[64:67]
	v_mfma_f32_16x16x32_bf16 v[56:59], v[176:179], v[200:203], v[56:59]
	v_mfma_f32_16x16x32_bf16 v[48:51], v[184:187], v[200:203], v[48:51]
	v_mfma_f32_16x16x32_bf16 v[44:47], v[176:179], v[208:211], v[44:47]
	v_mfma_f32_16x16x32_bf16 v[40:43], v[184:187], v[208:211], v[40:43]
	v_mfma_f32_16x16x32_bf16 v[36:39], v[176:179], v[216:219], v[36:39]
	v_mfma_f32_16x16x32_bf16 v[32:35], v[184:187], v[216:219], v[32:35]
	v_mfma_f32_16x16x32_bf16 v[68:71], v[180:183], v[196:199], v[68:71]
	v_mfma_f32_16x16x32_bf16 v[64:67], v[188:191], v[196:199], v[64:67]
	v_mfma_f32_16x16x32_bf16 v[56:59], v[180:183], v[204:207], v[56:59]
	v_mfma_f32_16x16x32_bf16 v[48:51], v[188:191], v[204:207], v[48:51]
	v_mfma_f32_16x16x32_bf16 v[44:47], v[180:183], v[212:215], v[44:47]
	v_mfma_f32_16x16x32_bf16 v[40:43], v[188:191], v[212:215], v[40:43]
	v_mfma_f32_16x16x32_bf16 v[36:39], v[180:183], v[220:223], v[36:39]
	v_mfma_f32_16x16x32_bf16 v[32:35], v[188:191], v[220:223], v[32:35]
	s_setprio 0
	s_barrier
; #define PG8_STAGE(bufoff, gbase, voff) do { _Pragma("unroll") for (int _i = 0; _i < 2; ++_i) \
;         __builtin_amdgcn_global_load_lds((const unsigned*)((const char*)(gbase) + (voff)[_i]), (PG8_LAS unsigned*)(lds + (bufoff) + ldsw + _i * 8192), 16, 0, 0); } while (0)
; #define PG8_LDA(dst, b, h) do { _Pragma("unroll") for (int m = 0; m < 4; ++m) _Pragma("unroll") for (int k = 0; k < 2; ++k) dst[m][k] = *(const PG8_LAS bf16x8*)(lds + PG8_SA(b, h) + aoff + m * 2048 + k * 1024); } while (0)
; #define PG8_MMA(ai, bj, At, Bt) do { __builtin_amdgcn_s_setprio(1); _Pragma("unroll") for (int m = 0; m < 4; ++m) _Pragma("unroll") for (int n = 0; n < 2; ++n) _Pragma("unroll") for (int k = 0; k < 2; ++k) \
;         acc[ai][bj][m][n] = __builtin_amdgcn_mfma_f32_16x16x32_bf16(Bt[n][k], At[m][k], acc[ai][bj][m][n], 0, 0, 0); __builtin_amdgcn_s_setprio(0); } while (0)
; #define PG8_WAIT_V(n) asm volatile("s_waitcnt vmcnt(" #n ")" ::: "memory")
; #define PG8_WAIT_L(n) asm volatile("s_waitcnt lgkmcnt(" #n ")" ::: "memory")
; #define PG8_BAR __builtin_amdgcn_s_barrier()
; #define PG8_SCHED __builtin_amdgcn_sched_barrier(0)
; template <class Epi, class Sched, bool ALIGN_EPI = false, bool SP2 = false>
; __device__ __forceinline__ void gemm_phase(PG8_LAS unsigned char* lds, const Gemm g, const Sched& S, const Epi& E) {
;     ...
;             PG8_LDA(At, 1, 1); PG8_STAGE(PG8_SB(1, 0), b3, voffB); PG8_STAGE(PG8_SB(1, 1), b3 + hstepB, voffB); PG8_STAGE(PG8_SA(1, 0), a3, voffA);
;             PG8_WAIT_V(8); PG8_WAIT_L(0); PG8_BAR; PG8_MMA(1, 0, At, B0); PG8_MMA(1, 1, At, B1); PG8_BAR; PG8_SCHED;
;     ...
;         if constexpr (ALIGN_EPI) { if (wr == 0) PG8_BAR; }
;         if constexpr (!Epi::AFTER_DRAIN) { E(acc, cur, wr, wc, fr, fq); S.done(cur); }
	s_add_i32 s75, s75, s27
	v_lshl_add_u64 v[224:225], v[224:225], 0, s[8:9]
	s_mov_b32 m0, s75
	ds_read_b128 v[192:195], v161 offset:49152
	ds_read_b128 v[196:199], v161 offset:50176
	ds_read_b128 v[200:203], v161 offset:51200
	ds_read_b128 v[204:207], v161 offset:52224
	ds_read_b128 v[208:211], v161 offset:53248
	ds_read_b128 v[212:215], v161 offset:54272
	ds_read_b128 v[216:219], v161 offset:55296
	ds_read_b128 v[220:223], v161 offset:56320
	global_load_lds_dwordx4 v[224:225], off
	s_add_i32 m0, s75, 0x2000
	s_add_u32 s66, s66, 0x40080
	v_lshl_add_u64 v[224:225], v[226:227], 0, s[8:9]
	s_addc_u32 s67, s67, 0
	s_add_i32 s33, s33, s27
	global_load_lds_dwordx4 v[224:225], off
	v_lshl_add_u64 v[224:225], s[66:67], 0, v[132:133]
	s_mov_b32 m0, s33
	s_nop 0
	global_load_lds_dwordx4 v[224:225], off
	v_lshl_add_u64 v[224:225], s[66:67], 0, v[128:129]
	s_add_i32 m0, s33, 0x2000
	s_nop 0
	global_load_lds_dwordx4 v[224:225], off
	v_lshl_add_u64 v[224:225], v[228:229], 0, s[8:9]
	s_mov_b32 m0, s91
	s_nop 0
	global_load_lds_dwordx4 v[224:225], off
	v_lshl_add_u64 v[224:225], v[230:231], 0, s[8:9]
	s_mov_b32 m0, s92
	s_nop 0
	global_load_lds_dwordx4 v[224:225], off
	s_waitcnt vmcnt(8)
	s_waitcnt lgkmcnt(0)
	s_barrier
	s_setprio 1
	s_waitcnt lgkmcnt(0)
	v_mfma_f32_16x16x32_bf16 v[92:95], v[146:149], v[192:195], v[92:95]
	v_mfma_f32_16x16x32_bf16 v[88:91], v[166:169], v[192:195], v[88:91]
	v_mfma_f32_16x16x32_bf16 v[84:87], v[146:149], v[200:203], v[84:87]
	v_mfma_f32_16x16x32_bf16 v[80:83], v[166:169], v[200:203], v[80:83]
	v_mfma_f32_16x16x32_bf16 v[76:79], v[146:149], v[208:211], v[76:79]
	v_mfma_f32_16x16x32_bf16 v[72:75], v[166:169], v[208:211], v[72:75]
	v_mfma_f32_16x16x32_bf16 v[60:63], v[146:149], v[216:219], v[60:63]
	v_mfma_f32_16x16x32_bf16 v[52:55], v[166:169], v[216:219], v[52:55]
	v_mfma_f32_16x16x32_bf16 v[92:95], v[162:165], v[196:199], v[92:95]
	v_mfma_f32_16x16x32_bf16 v[88:91], v[170:173], v[196:199], v[88:91]
	v_mfma_f32_16x16x32_bf16 v[84:87], v[162:165], v[204:207], v[84:87]
	v_mfma_f32_16x16x32_bf16 v[80:83], v[170:173], v[204:207], v[80:83]
	v_mfma_f32_16x16x32_bf16 v[76:79], v[162:165], v[212:215], v[76:79]
	v_mfma_f32_16x16x32_bf16 v[72:75], v[170:173], v[212:215], v[72:75]
	v_mfma_f32_16x16x32_bf16 v[60:63], v[162:165], v[220:223], v[60:63]
	v_mfma_f32_16x16x32_bf16 v[52:55], v[170:173], v[220:223], v[52:55]
	s_setprio 0
	s_setprio 1
	v_mfma_f32_16x16x32_bf16 v[28:31], v[176:179], v[192:195], v[28:31]
	v_mfma_f32_16x16x32_bf16 v[24:27], v[184:187], v[192:195], v[24:27]
	v_mfma_f32_16x16x32_bf16 v[20:23], v[176:179], v[200:203], v[20:23]
	v_mfma_f32_16x16x32_bf16 v[16:19], v[184:187], v[200:203], v[16:19]
	v_mfma_f32_16x16x32_bf16 v[12:15], v[176:179], v[208:211], v[12:15]
	v_mfma_f32_16x16x32_bf16 v[8:11], v[184:187], v[208:211], v[8:11]
	v_mfma_f32_16x16x32_bf16 v[4:7], v[176:179], v[216:219], v[4:7]
	v_mfma_f32_16x16x32_bf16 v[0:3], v[184:187], v[216:219], v[0:3]
	v_mfma_f32_16x16x32_bf16 v[28:31], v[180:183], v[196:199], v[28:31]
	v_mfma_f32_16x16x32_bf16 v[24:27], v[188:191], v[196:199], v[24:27]
	v_mfma_f32_16x16x32_bf16 v[20:23], v[180:183], v[204:207], v[20:23]
	v_mfma_f32_16x16x32_bf16 v[16:19], v[188:191], v[204:207], v[16:19]
	v_mfma_f32_16x16x32_bf16 v[12:15], v[180:183], v[212:215], v[12:15]
	v_mfma_f32_16x16x32_bf16 v[8:11], v[188:191], v[212:215], v[8:11]
	v_mfma_f32_16x16x32_bf16 v[4:7], v[180:183], v[220:223], v[4:7]
	v_mfma_f32_16x16x32_bf16 v[0:3], v[188:191], v[220:223], v[0:3]
	s_setprio 0
	s_barrier
	s_add_i32 s74, s74, 2
	s_add_u32 s60, s60, 0x100
	s_addc_u32 s61, s61, 0
	s_add_u32 s80, s80, 0x100
	s_addc_u32 s81, s81, 0
	s_cmp_gt_u32 s74, 13
	s_cbranch_scc0 .LBB0_197
	s_add_u32 s100, vcc_lo, 0x40080
	s_addc_u32 s101, s15, 0
	s_and_b64 vcc, exec, s[10:11]
	s_cbranch_vccnz .LBB0_203
	v_lshl_add_u64 v[224:225], s[100:101], 0, v[138:139]
	s_add_i32 m0, s59, 0xc000
	v_lshl_add_u64 v[226:227], s[100:101], 0, v[140:141]
	global_load_lds_dwordx4 v[224:225], off
	s_add_i32 m0, s59, 0xe000
	s_nop 0
	global_load_lds_dwordx4 v[226:227], off
	s_and_b32 s13, s73, -4
	s_cmp_lg_u32 s13, 4
	s_cbranch_scc0 .LBB0_204

; #define PG8_STAGE(bufoff, gbase, voff) do { _Pragma("unroll") for (int _i = 0; _i < 2; ++_i) \
;         __builtin_amdgcn_global_load_lds((const unsigned*)((const char*)(gbase) + (voff)[_i]), (PG8_LAS unsigned*)(lds + (bufoff) + ldsw + _i * 8192), 16, 0, 0); } while (0)
; #define PG8_LDA(dst, b, h) do { _Pragma("unroll") for (int m = 0; m < 4; ++m) _Pragma("unroll") for (int k = 0; k < 2; ++k) dst[m][k] = *(const PG8_LAS bf16x8*)(lds + PG8_SA(b, h) + aoff + m * 2048 + k * 1024); } while (0)
; #define PG8_LDB(dst, b, h) do { _Pragma("unroll") for (int n = 0; n < 2; ++n) _Pragma("unroll") for (int k = 0; k < 2; ++k) dst[n][k] = *(const PG8_LAS bf16x8*)(lds + PG8_SB(b, h) + boff + n * 2048 + k * 1024); } while (0)
; #define PG8_BAR __builtin_amdgcn_s_barrier()
; #define PG8_SCHED __builtin_amdgcn_sched_barrier(0)
; template <class Epi, class Sched, bool ALIGN_EPI = false, bool SP2 = false>
; __device__ __forceinline__ void gemm_phase(PG8_LAS unsigned char* lds, const Gemm g, const Sched& S, const Epi& E) {
;     ...
;             PG8_LDB(B0, 0, 0); PG8_LDB(B1, 0, 1); PG8_SCHED; PG8_LDA(At, 0, 0); PG8_STAGE(PG8_SA(1, 1), a1 + hstepA, voffA);
;     ...
;         if constexpr (ALIGN_EPI) { if (wr == 0) PG8_BAR; }
;         if constexpr (!Epi::AFTER_DRAIN) { E(acc, cur, wr, wc, fr, fq); S.done(cur); }
.LBB0_203:
	s_barrier
	v_lshl_add_u64 v[224:225], s[100:101], 0, v[138:139]
	s_add_i32 m0, s59, 0xc000
	v_lshl_add_u64 v[226:227], s[100:101], 0, v[140:141]
	global_load_lds_dwordx4 v[224:225], off
	s_add_i32 m0, s59, 0xe000
	s_nop 0
	global_load_lds_dwordx4 v[226:227], off
	s_and_b32 s13, s73, -4
	s_cmp_lg_u32 s13, 4
	s_cbranch_scc1 .LBB0_200

; #define PG8_STAGE(bufoff, gbase, voff) do { _Pragma("unroll") for (int _i = 0; _i < 2; ++_i) \
;         __builtin_amdgcn_global_load_lds((const unsigned*)((const char*)(gbase) + (voff)[_i]), (PG8_LAS unsigned*)(lds + (bufoff) + ldsw + _i * 8192), 16, 0, 0); } while (0)
; #define PG8_LDA(dst, b, h) do { _Pragma("unroll") for (int m = 0; m < 4; ++m) _Pragma("unroll") for (int k = 0; k < 2; ++k) dst[m][k] = *(const PG8_LAS bf16x8*)(lds + PG8_SA(b, h) + aoff + m * 2048 + k * 1024); } while (0)
; #define PG8_LDB(dst, b, h) do { _Pragma("unroll") for (int n = 0; n < 2; ++n) _Pragma("unroll") for (int k = 0; k < 2; ++k) dst[n][k] = *(const PG8_LAS bf16x8*)(lds + PG8_SB(b, h) + boff + n * 2048 + k * 1024); } while (0)
; #define PG8_MMA(ai, bj, At, Bt) do { __builtin_amdgcn_s_setprio(1); _Pragma("unroll") for (int m = 0; m < 4; ++m) _Pragma("unroll") for (int n = 0; n < 2; ++n) _Pragma("unroll") for (int k = 0; k < 2; ++k) \
;         acc[ai][bj][m][n] = __builtin_amdgcn_mfma_f32_16x16x32_bf16(Bt[n][k], At[m][k], acc[ai][bj][m][n], 0, 0, 0); __builtin_amdgcn_s_setprio(0); } while (0)
; #define PG8_WAIT_V(n) asm volatile("s_waitcnt vmcnt(" #n ")" ::: "memory")
; #define PG8_WAIT_L(n) asm volatile("s_waitcnt lgkmcnt(" #n ")" ::: "memory")
; #define PG8_BAR __builtin_amdgcn_s_barrier()
; #define PG8_SCHED __builtin_amdgcn_sched_barrier(0)
; template <class Epi, class Sched, bool ALIGN_EPI = false, bool SP2 = false>
; __device__ __forceinline__ void gemm_phase(PG8_LAS unsigned char* lds, const Gemm g, const Sched& S, const Epi& E) {
;     ...
;     f32x4 acc[2][2][4][2];
; #pragma unroll
;     for (int a = 0; a < 2; ++a)
; #pragma unroll
;         for (int b = 0; b < 2; ++b)
; #pragma unroll
;             for (int m = 0; m < 4; ++m)
; #pragma unroll
;                 for (int n = 0; n < 2; ++n) acc[a][b][m][n] = (f32x4){0.f, 0.f, 0.f, 0.f};
;     ...
;             PG8_LDB(B0, 0, 0); PG8_LDB(B1, 0, 1); PG8_SCHED; PG8_LDA(At, 0, 0); PG8_STAGE(PG8_SA(1, 1), a1 + hstepA, voffA);
;             PG8_WAIT_V(8); PG8_WAIT_L(0); PG8_BAR; PG8_MMA(0, 0, At, B0); PG8_MMA(0, 1, At, B1); PG8_BAR; PG8_SCHED;
;             PG8_LDA(At, 0, 1); PG8_STAGE(PG8_SB(0, 0), b2, voffB); PG8_STAGE(PG8_SB(0, 1), b2 + hstepB, voffB); PG8_STAGE(PG8_SA(0, 0), a2, voffA);
;             PG8_WAIT_V(8); PG8_WAIT_L(0); PG8_BAR; PG8_MMA(1, 0, At, B0); PG8_MMA(1, 1, At, B1); PG8_BAR; PG8_SCHED;
.Lpeel_p2:
	s_waitcnt lgkmcnt(0)
	ds_read_b128 v[146:149], v159
	ds_read_b128 v[162:165], v159 offset:1024
	ds_read_b128 v[166:169], v159 offset:2048
	ds_read_b128 v[170:173], v159 offset:3072
	ds_read_b128 v[176:179], v160
	ds_read_b128 v[180:183], v160 offset:1024
	ds_read_b128 v[184:187], v160 offset:2048
	ds_read_b128 v[188:191], v160 offset:3072
	s_add_u32 s66, s60, 0xfffc0080
	s_addc_u32 s67, s61, -1
	s_cmp_eq_u32 s74, 12
	s_cselect_b32 s85, s15, s67
	s_cselect_b32 s84, vcc_lo, s66
	s_cselect_b32 s67, s13, s81
	s_cselect_b32 s66, vcc_hi, s80
	ds_read_b128 v[192:195], v161
	ds_read_b128 v[196:199], v161 offset:1024
	ds_read_b128 v[200:203], v161 offset:2048
	ds_read_b128 v[204:207], v161 offset:3072
	ds_read_b128 v[208:211], v161 offset:4096
	ds_read_b128 v[212:215], v161 offset:5120
	ds_read_b128 v[216:219], v161 offset:6144
	ds_read_b128 v[220:223], v161 offset:7168
	s_waitcnt vmcnt(24)
	s_waitcnt lgkmcnt(0)
	s_barrier
	s_setprio 1
	s_waitcnt lgkmcnt(0)
	v_mfma_f32_16x16x32_bf16 v[124:127], v[146:149], v[192:195], 0
	v_mfma_f32_16x16x32_bf16 v[120:123], v[166:169], v[192:195], 0
	v_mfma_f32_16x16x32_bf16 v[116:119], v[146:149], v[200:203], 0
	v_mfma_f32_16x16x32_bf16 v[112:115], v[166:169], v[200:203], 0
	v_mfma_f32_16x16x32_bf16 v[108:111], v[146:149], v[208:211], 0
	v_mfma_f32_16x16x32_bf16 v[104:107], v[166:169], v[208:211], 0
	v_mfma_f32_16x16x32_bf16 v[100:103], v[146:149], v[216:219], 0
	v_mfma_f32_16x16x32_bf16 v[96:99], v[166:169], v[216:219], 0
	v_mfma_f32_16x16x32_bf16 v[124:127], v[162:165], v[196:199], v[124:127]
	v_mfma_f32_16x16x32_bf16 v[120:123], v[170:173], v[196:199], v[120:123]
	v_mfma_f32_16x16x32_bf16 v[116:119], v[162:165], v[204:207], v[116:119]
	v_mfma_f32_16x16x32_bf16 v[112:115], v[170:173], v[204:207], v[112:115]
	v_mfma_f32_16x16x32_bf16 v[108:111], v[162:165], v[212:215], v[108:111]
	v_mfma_f32_16x16x32_bf16 v[104:107], v[170:173], v[212:215], v[104:107]
	v_mfma_f32_16x16x32_bf16 v[100:103], v[162:165], v[220:223], v[100:103]
	v_mfma_f32_16x16x32_bf16 v[96:99], v[170:173], v[220:223], v[96:99]
	s_setprio 0
	s_setprio 1
	v_mfma_f32_16x16x32_bf16 v[68:71], v[176:179], v[192:195], 0
	v_mfma_f32_16x16x32_bf16 v[64:67], v[184:187], v[192:195], 0
	v_mfma_f32_16x16x32_bf16 v[56:59], v[176:179], v[200:203], 0
	v_mfma_f32_16x16x32_bf16 v[48:51], v[184:187], v[200:203], 0
	v_mfma_f32_16x16x32_bf16 v[44:47], v[176:179], v[208:211], 0
	v_mfma_f32_16x16x32_bf16 v[40:43], v[184:187], v[208:211], 0
	v_mfma_f32_16x16x32_bf16 v[36:39], v[176:179], v[216:219], 0
	v_mfma_f32_16x16x32_bf16 v[32:35], v[184:187], v[216:219], 0
	v_mfma_f32_16x16x32_bf16 v[68:71], v[180:183], v[196:199], v[68:71]
	v_mfma_f32_16x16x32_bf16 v[64:67], v[188:191], v[196:199], v[64:67]
	v_mfma_f32_16x16x32_bf16 v[56:59], v[180:183], v[204:207], v[56:59]
	v_mfma_f32_16x16x32_bf16 v[48:51], v[188:191], v[204:207], v[48:51]
	v_mfma_f32_16x16x32_bf16 v[44:47], v[180:183], v[212:215], v[44:47]
	v_mfma_f32_16x16x32_bf16 v[40:43], v[188:191], v[212:215], v[40:43]
	v_mfma_f32_16x16x32_bf16 v[36:39], v[180:183], v[220:223], v[36:39]
	v_mfma_f32_16x16x32_bf16 v[32:35], v[188:191], v[220:223], v[32:35]
	s_setprio 0
	s_barrier
	s_add_i32 s75, s38, s27
	v_lshl_add_u64 v[224:225], s[66:67], 0, v[132:133]
	s_mov_b32 m0, s75
	ds_read_b128 v[192:195], v161 offset:16384
	ds_read_b128 v[196:199], v161 offset:17408
	ds_read_b128 v[200:203], v161 offset:18432
	ds_read_b128 v[204:207], v161 offset:19456
	ds_read_b128 v[208:211], v161 offset:20480
	ds_read_b128 v[212:215], v161 offset:21504
	ds_read_b128 v[216:219], v161 offset:22528
	ds_read_b128 v[220:223], v161 offset:23552
	global_load_lds_dwordx4 v[224:225], off
	s_add_i32 m0, s75, 0x2000
	s_add_u32 s76, s66, 0x40000
	v_lshl_add_u64 v[226:227], s[66:67], 0, v[128:129]
	s_addc_u32 s77, s67, 0
	s_add_i32 s75, s39, s27
	global_load_lds_dwordx4 v[226:227], off
	v_lshl_add_u64 v[228:229], s[76:77], 0, v[132:133]
	s_mov_b32 m0, s75
	v_lshl_add_u64 v[230:231], s[84:85], 0, v[130:131]
	global_load_lds_dwordx4 v[228:229], off
	v_lshl_add_u64 v[228:229], s[76:77], 0, v[128:129]
	s_add_i32 m0, s75, 0x2000
	s_nop 0
	global_load_lds_dwordx4 v[228:229], off
	v_lshl_add_u64 v[228:229], s[84:85], 0, v[134:135]
	s_mov_b32 m0, s59
	s_nop 0
	global_load_lds_dwordx4 v[228:229], off
	s_mov_b32 m0, s86
	s_nop 0
	global_load_lds_dwordx4 v[230:231], off
	s_waitcnt vmcnt(24)
	s_waitcnt lgkmcnt(0)
	s_barrier
	s_setprio 1
	s_waitcnt lgkmcnt(0)
	v_mfma_f32_16x16x32_bf16 v[92:95], v[146:149], v[192:195], 0
	v_mfma_f32_16x16x32_bf16 v[88:91], v[166:169], v[192:195], 0
	v_mfma_f32_16x16x32_bf16 v[84:87], v[146:149], v[200:203], 0
	v_mfma_f32_16x16x32_bf16 v[80:83], v[166:169], v[200:203], 0
	v_mfma_f32_16x16x32_bf16 v[76:79], v[146:149], v[208:211], 0
	v_mfma_f32_16x16x32_bf16 v[72:75], v[166:169], v[208:211], 0
	v_mfma_f32_16x16x32_bf16 v[60:63], v[146:149], v[216:219], 0
	v_mfma_f32_16x16x32_bf16 v[52:55], v[166:169], v[216:219], 0
	v_mfma_f32_16x16x32_bf16 v[92:95], v[162:165], v[196:199], v[92:95]
	v_mfma_f32_16x16x32_bf16 v[88:91], v[170:173], v[196:199], v[88:91]
	v_mfma_f32_16x16x32_bf16 v[84:87], v[162:165], v[204:207], v[84:87]
	v_mfma_f32_16x16x32_bf16 v[80:83], v[170:173], v[204:207], v[80:83]
	v_mfma_f32_16x16x32_bf16 v[76:79], v[162:165], v[212:215], v[76:79]
	v_mfma_f32_16x16x32_bf16 v[72:75], v[170:173], v[212:215], v[72:75]
	v_mfma_f32_16x16x32_bf16 v[60:63], v[162:165], v[220:223], v[60:63]
	v_mfma_f32_16x16x32_bf16 v[52:55], v[170:173], v[220:223], v[52:55]
	s_setprio 0
	s_setprio 1
	v_mfma_f32_16x16x32_bf16 v[28:31], v[176:179], v[192:195], 0
	v_mfma_f32_16x16x32_bf16 v[24:27], v[184:187], v[192:195], 0
	v_mfma_f32_16x16x32_bf16 v[20:23], v[176:179], v[200:203], 0
	v_mfma_f32_16x16x32_bf16 v[16:19], v[184:187], v[200:203], 0
	v_mfma_f32_16x16x32_bf16 v[12:15], v[176:179], v[208:211], 0
	v_mfma_f32_16x16x32_bf16 v[8:11], v[184:187], v[208:211], 0
	v_mfma_f32_16x16x32_bf16 v[4:7], v[176:179], v[216:219], 0
	v_mfma_f32_16x16x32_bf16 v[0:3], v[184:187], v[216:219], 0
	v_mfma_f32_16x16x32_bf16 v[28:31], v[180:183], v[196:199], v[28:31]
	v_mfma_f32_16x16x32_bf16 v[24:27], v[188:191], v[196:199], v[24:27]
	v_mfma_f32_16x16x32_bf16 v[20:23], v[180:183], v[204:207], v[20:23]
	v_mfma_f32_16x16x32_bf16 v[16:19], v[188:191], v[204:207], v[16:19]
	v_mfma_f32_16x16x32_bf16 v[12:15], v[180:183], v[212:215], v[12:15]
	v_mfma_f32_16x16x32_bf16 v[8:11], v[188:191], v[212:215], v[8:11]
	v_mfma_f32_16x16x32_bf16 v[4:7], v[180:183], v[220:223], v[4:7]
	v_mfma_f32_16x16x32_bf16 v[0:3], v[188:191], v[220:223], v[0:3]
	s_setprio 0
	s_barrier
; #define PG8_STAGE(bufoff, gbase, voff) do { _Pragma("unroll") for (int _i = 0; _i < 2; ++_i) \
;         __builtin_amdgcn_global_load_lds((const unsigned*)((const char*)(gbase) + (voff)[_i]), (PG8_LAS unsigned*)(lds + (bufoff) + ldsw + _i * 8192), 16, 0, 0); } while (0)
; #define PG8_LDA(dst, b, h) do { _Pragma("unroll") for (int m = 0; m < 4; ++m) _Pragma("unroll") for (int k = 0; k < 2; ++k) dst[m][k] = *(const PG8_LAS bf16x8*)(lds + PG8_SA(b, h) + aoff + m * 2048 + k * 1024); } while (0)
; #define PG8_LDB(dst, b, h) do { _Pragma("unroll") for (int n = 0; n < 2; ++n) _Pragma("unroll") for (int k = 0; k < 2; ++k) dst[n][k] = *(const PG8_LAS bf16x8*)(lds + PG8_SB(b, h) + boff + n * 2048 + k * 1024); } while (0)
; #define PG8_MMA(ai, bj, At, Bt) do { __builtin_amdgcn_s_setprio(1); _Pragma("unroll") for (int m = 0; m < 4; ++m) _Pragma("unroll") for (int n = 0; n < 2; ++n) _Pragma("unroll") for (int k = 0; k < 2; ++k) \
;         acc[ai][bj][m][n] = __builtin_amdgcn_mfma_f32_16x16x32_bf16(Bt[n][k], At[m][k], acc[ai][bj][m][n], 0, 0, 0); __builtin_amdgcn_s_setprio(0); } while (0)
; #define PG8_WAIT_V(n) asm volatile("s_waitcnt vmcnt(" #n ")" ::: "memory")
; #define PG8_WAIT_L(n) asm volatile("s_waitcnt lgkmcnt(" #n ")" ::: "memory")
; #define PG8_BAR __builtin_amdgcn_s_barrier()
; #define PG8_SCHED __builtin_amdgcn_sched_barrier(0)
; template <class Epi, class Sched, bool ALIGN_EPI = false, bool SP2 = false>
; __device__ __forceinline__ void gemm_phase(PG8_LAS unsigned char* lds, const Gemm g, const Sched& S, const Epi& E) {
;     ...
;             PG8_LDB(B0, 1, 0); PG8_LDB(B1, 1, 1); PG8_SCHED; PG8_LDA(At, 1, 0); PG8_STAGE(PG8_SA(0, 1), a2 + hstepA, voffA);
;             PG8_WAIT_V(8); PG8_WAIT_L(0); PG8_BAR; PG8_MMA(0, 0, At, B0); PG8_MMA(0, 1, At, B1); PG8_BAR; PG8_SCHED;
	s_add_i32 s75, 0, 0x18000
	s_add_i32 s33, 0, 0x1c000
	v_add_u32_e32 v170, s75, v151
	v_add_u32_e32 v175, s33, v151
	ds_read_b128 v[146:149], v170
	ds_read_b128 v[162:165], v170 offset:1024
	ds_read_b128 v[166:169], v170 offset:2048
	ds_read_b128 v[170:173], v170 offset:3072
	ds_read_b128 v[176:179], v175
	ds_read_b128 v[180:183], v175 offset:1024
	ds_read_b128 v[184:187], v175 offset:2048
	ds_read_b128 v[188:191], v175 offset:3072
	s_add_u32 s76, s84, 0x40000
	s_addc_u32 s77, s85, 0
	s_mov_b32 m0, s87
	v_lshl_add_u64 v[232:233], s[76:77], 0, v[134:135]
	ds_read_b128 v[192:195], v161 offset:32768
	ds_read_b128 v[196:199], v161 offset:33792
	ds_read_b128 v[200:203], v161 offset:34816
	ds_read_b128 v[204:207], v161 offset:35840
	ds_read_b128 v[208:211], v161 offset:36864
	ds_read_b128 v[212:215], v161 offset:37888
	ds_read_b128 v[216:219], v161 offset:38912
	ds_read_b128 v[220:223], v161 offset:39936
	global_load_lds_dwordx4 v[232:233], off
	v_lshl_add_u64 v[232:233], s[76:77], 0, v[130:131]
	s_mov_b32 m0, s88
	s_nop 0
	global_load_lds_dwordx4 v[232:233], off
	s_waitcnt vmcnt(24)
	s_waitcnt lgkmcnt(0)
	s_barrier
	s_setprio 1
	s_waitcnt lgkmcnt(0)
	v_mfma_f32_16x16x32_bf16 v[124:127], v[146:149], v[192:195], v[124:127]
	v_mfma_f32_16x16x32_bf16 v[120:123], v[166:169], v[192:195], v[120:123]
	v_mfma_f32_16x16x32_bf16 v[116:119], v[146:149], v[200:203], v[116:119]
	v_mfma_f32_16x16x32_bf16 v[112:115], v[166:169], v[200:203], v[112:115]
	v_mfma_f32_16x16x32_bf16 v[108:111], v[146:149], v[208:211], v[108:111]
	v_mfma_f32_16x16x32_bf16 v[104:107], v[166:169], v[208:211], v[104:107]
	v_mfma_f32_16x16x32_bf16 v[100:103], v[146:149], v[216:219], v[100:103]
	v_mfma_f32_16x16x32_bf16 v[96:99], v[166:169], v[216:219], v[96:99]
	v_mfma_f32_16x16x32_bf16 v[124:127], v[162:165], v[196:199], v[124:127]
	v_mfma_f32_16x16x32_bf16 v[120:123], v[170:173], v[196:199], v[120:123]
	v_mfma_f32_16x16x32_bf16 v[116:119], v[162:165], v[204:207], v[116:119]
	v_mfma_f32_16x16x32_bf16 v[112:115], v[170:173], v[204:207], v[112:115]
	v_mfma_f32_16x16x32_bf16 v[108:111], v[162:165], v[212:215], v[108:111]
	v_mfma_f32_16x16x32_bf16 v[104:107], v[170:173], v[212:215], v[104:107]
	v_mfma_f32_16x16x32_bf16 v[100:103], v[162:165], v[220:223], v[100:103]
	v_mfma_f32_16x16x32_bf16 v[96:99], v[170:173], v[220:223], v[96:99]
	s_setprio 0
	s_setprio 1
	v_mfma_f32_16x16x32_bf16 v[68:71], v[176:179], v[192:195], v[68:71]
	v_mfma_f32_16x16x32_bf16 v[64:67], v[184:187], v[192:195], v[64:67]
	v_mfma_f32_16x16x32_bf16 v[56:59], v[176:179], v[200:203], v[56:59]
	v_mfma_f32_16x16x32_bf16 v[48:51], v[184:187], v[200:203], v[48:51]
	v_mfma_f32_16x16x32_bf16 v[44:47], v[176:179], v[208:211], v[44:47]
	v_mfma_f32_16x16x32_bf16 v[40:43], v[184:187], v[208:211], v[40:43]
	v_mfma_f32_16x16x32_bf16 v[36:39], v[176:179], v[216:219], v[36:39]
	v_mfma_f32_16x16x32_bf16 v[32:35], v[184:187], v[216:219], v[32:35]
	v_mfma_f32_16x16x32_bf16 v[68:71], v[180:183], v[196:199], v[68:71]
	v_mfma_f32_16x16x32_bf16 v[64:67], v[188:191], v[196:199], v[64:67]
	v_mfma_f32_16x16x32_bf16 v[56:59], v[180:183], v[204:207], v[56:59]
	v_mfma_f32_16x16x32_bf16 v[48:51], v[188:191], v[204:207], v[48:51]
	v_mfma_f32_16x16x32_bf16 v[44:47], v[180:183], v[212:215], v[44:47]
	v_mfma_f32_16x16x32_bf16 v[40:43], v[188:191], v[212:215], v[40:43]
	v_mfma_f32_16x16x32_bf16 v[36:39], v[180:183], v[220:223], v[36:39]
	v_mfma_f32_16x16x32_bf16 v[32:35], v[188:191], v[220:223], v[32:35]
	s_setprio 0
	s_barrier
; #define PG8_STAGE(bufoff, gbase, voff) do { _Pragma("unroll") for (int _i = 0; _i < 2; ++_i) \
;         __builtin_amdgcn_global_load_lds((const unsigned*)((const char*)(gbase) + (voff)[_i]), (PG8_LAS unsigned*)(lds + (bufoff) + ldsw + _i * 8192), 16, 0, 0); } while (0)
; #define PG8_LDA(dst, b, h) do { _Pragma("unroll") for (int m = 0; m < 4; ++m) _Pragma("unroll") for (int k = 0; k < 2; ++k) dst[m][k] = *(const PG8_LAS bf16x8*)(lds + PG8_SA(b, h) + aoff + m * 2048 + k * 1024); } while (0)
; #define PG8_MMA(ai, bj, At, Bt) do { __builtin_amdgcn_s_setprio(1); _Pragma("unroll") for (int m = 0; m < 4; ++m) _Pragma("unroll") for (int n = 0; n < 2; ++n) _Pragma("unroll") for (int k = 0; k < 2; ++k) \
;         acc[ai][bj][m][n] = __builtin_amdgcn_mfma_f32_16x16x32_bf16(Bt[n][k], At[m][k], acc[ai][bj][m][n], 0, 0, 0); __builtin_amdgcn_s_setprio(0); } while (0)
; #define PG8_WAIT_V(n) asm volatile("s_waitcnt vmcnt(" #n ")" ::: "memory")
; #define PG8_WAIT_L(n) asm volatile("s_waitcnt lgkmcnt(" #n ")" ::: "memory")
; #define PG8_BAR __builtin_amdgcn_s_barrier()
; #define PG8_SCHED __builtin_amdgcn_sched_barrier(0)
; template <class Epi, class Sched, bool ALIGN_EPI = false, bool SP2 = false>
; __device__ __forceinline__ void gemm_phase(PG8_LAS unsigned char* lds, const Gemm g, const Sched& S, const Epi& E) {
;     ...
;         for (int t = 0; t < nt; t += 2) {
;     ...
;             PG8_LDA(At, 1, 1); PG8_STAGE(PG8_SB(1, 0), b3, voffB); PG8_STAGE(PG8_SB(1, 1), b3 + hstepB, voffB); PG8_STAGE(PG8_SA(1, 0), a3, voffA);
;             PG8_WAIT_V(8); PG8_WAIT_L(0); PG8_BAR; PG8_MMA(1, 0, At, B0); PG8_MMA(1, 1, At, B1); PG8_BAR; PG8_SCHED;
	s_add_i32 s75, s75, s27
	v_lshl_add_u64 v[224:225], v[224:225], 0, s[8:9]
	s_mov_b32 m0, s75
	ds_read_b128 v[192:195], v161 offset:49152
	ds_read_b128 v[196:199], v161 offset:50176
	ds_read_b128 v[200:203], v161 offset:51200
	ds_read_b128 v[204:207], v161 offset:52224
	ds_read_b128 v[208:211], v161 offset:53248
	ds_read_b128 v[212:215], v161 offset:54272
	ds_read_b128 v[216:219], v161 offset:55296
	ds_read_b128 v[220:223], v161 offset:56320
	global_load_lds_dwordx4 v[224:225], off
	s_add_i32 m0, s75, 0x2000
	s_add_u32 s66, s66, 0x40080
	v_lshl_add_u64 v[224:225], v[226:227], 0, s[8:9]
	s_addc_u32 s67, s67, 0
	s_add_i32 s33, s33, s27
	global_load_lds_dwordx4 v[224:225], off
	v_lshl_add_u64 v[224:225], s[66:67], 0, v[132:133]
	s_mov_b32 m0, s33
	s_nop 0
	global_load_lds_dwordx4 v[224:225], off
	v_lshl_add_u64 v[224:225], s[66:67], 0, v[128:129]
	s_add_i32 m0, s33, 0x2000
	s_nop 0
	global_load_lds_dwordx4 v[224:225], off
	v_lshl_add_u64 v[224:225], v[228:229], 0, s[8:9]
	s_mov_b32 m0, s91
	s_nop 0
	global_load_lds_dwordx4 v[224:225], off
	v_lshl_add_u64 v[224:225], v[230:231], 0, s[8:9]
	s_mov_b32 m0, s92
	s_nop 0
	global_load_lds_dwordx4 v[224:225], off
	s_waitcnt vmcnt(8)
	s_waitcnt lgkmcnt(0)
	s_barrier
	s_setprio 1
	s_waitcnt lgkmcnt(0)
	v_mfma_f32_16x16x32_bf16 v[92:95], v[146:149], v[192:195], v[92:95]
	v_mfma_f32_16x16x32_bf16 v[88:91], v[166:169], v[192:195], v[88:91]
	v_mfma_f32_16x16x32_bf16 v[84:87], v[146:149], v[200:203], v[84:87]
	v_mfma_f32_16x16x32_bf16 v[80:83], v[166:169], v[200:203], v[80:83]
	v_mfma_f32_16x16x32_bf16 v[76:79], v[146:149], v[208:211], v[76:79]
	v_mfma_f32_16x16x32_bf16 v[72:75], v[166:169], v[208:211], v[72:75]
	v_mfma_f32_16x16x32_bf16 v[60:63], v[146:149], v[216:219], v[60:63]
	v_mfma_f32_16x16x32_bf16 v[52:55], v[166:169], v[216:219], v[52:55]
	v_mfma_f32_16x16x32_bf16 v[92:95], v[162:165], v[196:199], v[92:95]
	v_mfma_f32_16x16x32_bf16 v[88:91], v[170:173], v[196:199], v[88:91]
	v_mfma_f32_16x16x32_bf16 v[84:87], v[162:165], v[204:207], v[84:87]
	v_mfma_f32_16x16x32_bf16 v[80:83], v[170:173], v[204:207], v[80:83]
	v_mfma_f32_16x16x32_bf16 v[76:79], v[162:165], v[212:215], v[76:79]
	v_mfma_f32_16x16x32_bf16 v[72:75], v[170:173], v[212:215], v[72:75]
	v_mfma_f32_16x16x32_bf16 v[60:63], v[162:165], v[220:223], v[60:63]
	v_mfma_f32_16x16x32_bf16 v[52:55], v[170:173], v[220:223], v[52:55]
	s_setprio 0
	s_setprio 1
	v_mfma_f32_16x16x32_bf16 v[28:31], v[176:179], v[192:195], v[28:31]
	v_mfma_f32_16x16x32_bf16 v[24:27], v[184:187], v[192:195], v[24:27]
	v_mfma_f32_16x16x32_bf16 v[20:23], v[176:179], v[200:203], v[20:23]
	v_mfma_f32_16x16x32_bf16 v[16:19], v[184:187], v[200:203], v[16:19]
	v_mfma_f32_16x16x32_bf16 v[12:15], v[176:179], v[208:211], v[12:15]
	v_mfma_f32_16x16x32_bf16 v[8:11], v[184:187], v[208:211], v[8:11]
	v_mfma_f32_16x16x32_bf16 v[4:7], v[176:179], v[216:219], v[4:7]
	v_mfma_f32_16x16x32_bf16 v[0:3], v[184:187], v[216:219], v[0:3]
	v_mfma_f32_16x16x32_bf16 v[28:31], v[180:183], v[196:199], v[28:31]
	v_mfma_f32_16x16x32_bf16 v[24:27], v[188:191], v[196:199], v[24:27]
	v_mfma_f32_16x16x32_bf16 v[20:23], v[180:183], v[204:207], v[20:23]
	v_mfma_f32_16x16x32_bf16 v[16:19], v[188:191], v[204:207], v[16:19]
	v_mfma_f32_16x16x32_bf16 v[12:15], v[180:183], v[212:215], v[12:15]
	v_mfma_f32_16x16x32_bf16 v[8:11], v[188:191], v[212:215], v[8:11]
	v_mfma_f32_16x16x32_bf16 v[4:7], v[180:183], v[220:223], v[4:7]
	v_mfma_f32_16x16x32_bf16 v[0:3], v[188:191], v[220:223], v[0:3]
	s_setprio 0
	s_barrier
	s_add_i32 s74, s74, 2
	s_add_u32 s60, s60, 0x100
	s_addc_u32 s61, s61, 0
	s_add_u32 s80, s80, 0x100
	s_addc_u32 s81, s81, 0
	s_cmp_gt_u32 s74, 13
	s_branch .LBB0_197

; __device__ __forceinline__ void attn_unit_pp(int b, int h, int qb, int par, const bf16_t* __restrict__ QBp, const bf16_t* __restrict__ KBp, const bf16_t* __restrict__ VBp, ...
;     ...
;     unsigned gate16[64];
; #pragma unroll
;     for (int r = 0; r < 16; ++r)
; #pragma unroll
;       for (int d0 = 0; d0 < 4; ++d0) gate16[r * 4 + d0] = GATE_LD((r & 3) + 8 * (r >> 2), d0 * 32);
;     __syncthreads();
.LBB0_411:
	v_add_u32_e32 v36, 64, v34
	v_add_u32_e32 v37, 0x80, v34
	v_add_u32_e32 v38, 0xc0, v34
	v_add_u32_e32 v39, 0x1000, v34
	v_add_u32_e32 v40, 0x1040, v34
	v_add_u32_e32 v41, 0x1080, v34
	v_add_u32_e32 v42, 0x10c0, v34
	global_load_ushort v165, v34, s[20:21]
	global_load_ushort v163, v36, s[20:21]
	global_load_ushort v162, v37, s[20:21]
	global_load_ushort v159, v38, s[20:21]
	global_load_ushort v157, v39, s[20:21]
	global_load_ushort v154, v40, s[20:21]
	global_load_ushort v152, v41, s[20:21]
	global_load_ushort v149, v42, s[20:21]
	v_add_u32_e32 v36, 0x2000, v34
	v_add_u32_e32 v37, 0x2040, v34
	v_add_u32_e32 v38, 0x2080, v34
	v_add_u32_e32 v39, 0x20c0, v34
	v_add_u32_e32 v43, 0x30c0, v34
	v_add_u32_e32 v40, 0x3000, v34
	v_add_u32_e32 v41, 0x3040, v34
	v_add_u32_e32 v42, 0x3080, v34
	global_load_ushort v151, v36, s[20:21]
	global_load_ushort v148, v37, s[20:21]
	global_load_ushort v147, v38, s[20:21]
	global_load_ushort v143, v39, s[20:21]
	global_load_ushort v141, v40, s[20:21]
	global_load_ushort v139, v41, s[20:21]
	global_load_ushort v138, v42, s[20:21]
	global_load_ushort v134, v43, s[20:21]
	v_add_u32_e32 v36, 0x8000, v34
	v_add_u32_e32 v37, 0x8040, v34
	v_add_u32_e32 v38, 0x8080, v34
	v_add_u32_e32 v39, 0x80c0, v34
	v_add_u32_e32 v43, 0x90c0, v34
	v_add_u32_e32 v40, 0x9000, v34
	v_add_u32_e32 v41, 0x9040, v34
	v_add_u32_e32 v42, 0x9080, v34
	global_load_ushort v137, v36, s[20:21]
	global_load_ushort v133, v37, s[20:21]
	global_load_ushort v131, v38, s[20:21]
	global_load_ushort v130, v39, s[20:21]
	global_load_ushort v129, v40, s[20:21]
	global_load_ushort v126, v41, s[20:21]
	global_load_ushort v124, v42, s[20:21]
	global_load_ushort v122, v43, s[20:21]
	v_add_u32_e32 v36, 0xa000, v34
	v_add_u32_e32 v37, 0xa040, v34
	v_add_u32_e32 v38, 0xa080, v34
	v_add_u32_e32 v39, 0xa0c0, v34
	v_add_u32_e32 v43, 0xb0c0, v34
	v_add_u32_e32 v40, 0xb000, v34
	v_add_u32_e32 v41, 0xb040, v34
	v_add_u32_e32 v42, 0xb080, v34
	global_load_ushort v123, v36, s[20:21]
	global_load_ushort v121, v37, s[20:21]
	global_load_ushort v120, v38, s[20:21]
	global_load_ushort v117, v39, s[20:21]
	global_load_ushort v115, v40, s[20:21]
	global_load_ushort v114, v41, s[20:21]
	global_load_ushort v113, v42, s[20:21]
	global_load_ushort v109, v43, s[20:21]
	v_add_u32_e32 v36, 0x10000, v34
	v_add_u32_e32 v37, 0x10040, v34
	v_add_u32_e32 v38, 0x10080, v34
	v_add_u32_e32 v39, 0x100c0, v34
	v_add_u32_e32 v43, 0x110c0, v34
	v_add_u32_e32 v40, 0x11000, v34
	v_add_u32_e32 v41, 0x11040, v34
	v_add_u32_e32 v42, 0x11080, v34
	global_load_ushort v110, v36, s[20:21]
	global_load_ushort v108, v37, s[20:21]
	global_load_ushort v106, v38, s[20:21]
	global_load_ushort v105, v39, s[20:21]
	global_load_ushort v104, v40, s[20:21]
	global_load_ushort v102, v41, s[20:21]
	global_load_ushort v65, v42, s[20:21]
	global_load_ushort v63, v43, s[20:21]
	v_add_u32_e32 v36, 0x12000, v34
	v_add_u32_e32 v37, 0x12040, v34
	v_add_u32_e32 v38, 0x12080, v34
	v_add_u32_e32 v39, 0x120c0, v34
	v_add_u32_e32 v43, 0x130c0, v34
	v_add_u32_e32 v40, 0x13000, v34
	v_add_u32_e32 v41, 0x13040, v34
	v_add_u32_e32 v42, 0x13080, v34
	global_load_ushort v64, v36, s[20:21]
	global_load_ushort v62, v37, s[20:21]
	global_load_ushort v60, v38, s[20:21]
	global_load_ushort v59, v39, s[20:21]
	global_load_ushort v57, v40, s[20:21]
	global_load_ushort v56, v41, s[20:21]
	global_load_ushort v55, v42, s[20:21]
	global_load_ushort v53, v43, s[20:21]
	v_add_u32_e32 v36, 0x18000, v34
	v_add_u32_e32 v37, 0x18040, v34
	v_add_u32_e32 v38, 0x18080, v34
	v_add_u32_e32 v39, 0x180c0, v34
	v_add_u32_e32 v43, 0x190c0, v34
	v_add_u32_e32 v40, 0x19000, v34
	v_add_u32_e32 v41, 0x19040, v34
	v_add_u32_e32 v42, 0x19080, v34
	global_load_ushort v54, v36, s[20:21]
	global_load_ushort v52, v37, s[20:21]
	global_load_ushort v50, v38, s[20:21]
	global_load_ushort v49, v39, s[20:21]
	global_load_ushort v48, v40, s[20:21]
	global_load_ushort v47, v41, s[20:21]
	global_load_ushort v45, v42, s[20:21]
	s_nop 0
	global_load_ushort v43, v43, s[20:21]
	v_add_u32_e32 v36, 0x1a000, v34
	v_add_u32_e32 v37, 0x1a040, v34
	v_add_u32_e32 v38, 0x1a080, v34
	v_add_u32_e32 v39, 0x1a0c0, v34
	v_add_u32_e32 v46, 0x1b000, v34
	v_add_u32_e32 v51, 0x1b040, v34
	v_add_u32_e32 v58, 0x1b080, v34
	v_add_u32_e32 v61, 0x1b0c0, v34
	global_load_ushort v44, v36, s[20:21]
	global_load_ushort v42, v37, s[20:21]
	global_load_ushort v41, v38, s[20:21]
	global_load_ushort v40, v39, s[20:21]
	s_nop 0
	global_load_ushort v39, v46, s[20:21]
	global_load_ushort v38, v51, s[20:21]
	global_load_ushort v37, v58, s[20:21]
	global_load_ushort v36, v61, s[20:21]
	s_waitcnt vmcnt(63) expcnt(7) lgkmcnt(15)
	s_barrier
; __device__ __forceinline__ void attn_unit_pp(int b, int h, int qb, int par, const bf16_t* __restrict__ QBp, const bf16_t* __restrict__ KBp, const bf16_t* __restrict__ VBp, ...
;     ...
;     for (int d0 = 0; d0 < 4; ++d0)
; #pragma unroll
;       for (int r = 0; r < 16; ++r) { const float v = o[d0][r] - lam * xs[(d0 * 16 + r) * 64]; o[d0][r] = v; ss[r] += v * v; }
; #pragma unroll
;     for (int r = 0; r < 16; ++r) { float s = ss[r];
; #pragma unroll
;       for (int x = 1; x < 32; x <<= 1) s += __builtin_bit_cast(float, __builtin_amdgcn_ds_bpermute((lane ^ x) << 2, __builtin_bit_cast(int, s)));
;       ss[r] = 1.0f / sqrtf(s * (1.0f / 128.0f) + 1e-5f); }
	ds_read2st64_b32 v[118:119], v78 offset1:1
	ds_read2st64_b32 v[144:145], v78 offset0:2 offset1:3
	ds_read2st64_b32 v[160:161], v78 offset0:4 offset1:5
	ds_read2st64_b32 v[172:173], v78 offset0:6 offset1:7
	s_waitcnt lgkmcnt(3)
	v_fma_f32 v198, -v175, v118, v9
	v_fma_f32 v194, -v175, v119, v13
	s_waitcnt lgkmcnt(2)
	v_fma_f32 v190, -v175, v144, v17
	v_fma_f32 v186, -v175, v145, v32
	s_waitcnt lgkmcnt(0)
	v_fma_f32 v150, -v175, v172, v82
	ds_read2st64_b32 v[118:119], v78 offset0:8 offset1:9
	v_fma_f32 v140, -v175, v173, v22
	ds_read2st64_b32 v[144:145], v78 offset0:10 offset1:11
	ds_read2st64_b32 v[172:173], v78 offset0:12 offset1:13
	ds_read2st64_b32 v[184:185], v78 offset0:14 offset1:15
	v_fma_f32 v171, -v175, v160, v67
	v_fma_f32 v161, -v175, v161, v80
	s_waitcnt lgkmcnt(3)
	v_fma_f32 v132, -v175, v118, v86
	v_fma_f32 v125, -v175, v119, v88
	s_waitcnt lgkmcnt(2)
	v_fma_f32 v116, -v175, v144, v90
	v_fma_f32 v107, -v175, v145, v91
	s_waitcnt lgkmcnt(1)
	v_fma_f32 v101, -v175, v172, v93
	v_fma_f32 v58, -v175, v173, v96
	s_waitcnt lgkmcnt(0)
	v_fma_f32 v51, -v175, v184, v98
	ds_read2st64_b32 v[118:119], v78 offset0:16 offset1:17
	v_fma_f32 v46, -v175, v185, v100
	ds_read2st64_b32 v[144:145], v78 offset0:18 offset1:19
	ds_read2st64_b32 v[172:173], v78 offset0:20 offset1:21
	ds_read2st64_b32 v[184:185], v78 offset0:22 offset1:23
	s_waitcnt vmcnt(62)
	v_lshlrev_b32_e32 v163, 16, v163
	v_mul_f32_e32 v163, 0xbfb8aa3b, v163
	s_waitcnt lgkmcnt(3)
	v_fma_f32 v202, -v175, v118, v6
	v_fma_f32 v199, -v175, v119, v10
	s_waitcnt lgkmcnt(0)
	v_fma_f32 v167, -v175, v184, v70
	v_fma_f32 v158, -v175, v185, v83
	ds_read2st64_b32 v[118:119], v78 offset0:24 offset1:25
	ds_read2st64_b32 v[184:185], v78 offset0:26 offset1:27
	ds_read2st64_b32 v[188:189], v78 offset0:28 offset1:29
	ds_read2st64_b32 v[192:193], v78 offset0:30 offset1:31
	v_fma_f32 v187, -v175, v172, v33
	v_fma_f32 v172, -v175, v173, v69
	s_waitcnt lgkmcnt(2)
	v_fma_f32 v135, -v175, v184, v87
	v_fma_f32 v155, -v175, v118, v84
	v_fma_f32 v127, -v175, v185, v89
	s_waitcnt lgkmcnt(1)
	v_fma_f32 v118, -v175, v188, v92
	v_fma_f32 v111, -v175, v189, v94
	s_waitcnt lgkmcnt(0)
	v_fma_f32 v103, -v175, v192, v97
	v_fma_f32 v61, -v175, v193, v99
	ds_read2st64_b32 v[184:185], v78 offset0:32 offset1:33
	ds_read2st64_b32 v[188:189], v78 offset0:34 offset1:35
	ds_read2st64_b32 v[192:193], v78 offset0:36 offset1:37
	ds_read2st64_b32 v[226:227], v78 offset0:38 offset1:39
	v_mul_f32_e32 v142, v202, v202
	v_fmac_f32_e32 v142, v198, v198
	s_waitcnt lgkmcnt(2)
	v_fma_f32 v205, -v175, v188, v11
	v_fma_f32 v209, -v175, v184, v4
	s_waitcnt lgkmcnt(0)
	v_fma_f32 v188, -v175, v226, v81
	v_fma_f32 v184, -v175, v227, v71
	ds_read2st64_b32 v[226:227], v78 offset0:40 offset1:41
	ds_read2st64_b32 v[228:229], v78 offset0:42 offset1:43
	ds_read2st64_b32 v[230:231], v78 offset0:44 offset1:45
	ds_read2st64_b32 v[232:233], v78 offset0:46 offset1:47
	v_fmac_f32_e32 v142, v209, v209
	v_fma_f32 v195, -v175, v144, v14
	v_fma_f32 v191, -v175, v145, v18
	s_waitcnt lgkmcnt(3)
	v_fma_f32 v173, -v175, v226, v72
	v_fma_f32 v164, -v175, v227, v73
	ds_read2st64_b32 v[226:227], v78 offset0:48 offset1:49
	v_fma_f32 v145, -v175, v119, v85
	s_waitcnt lgkmcnt(3)
	v_fma_f32 v156, -v175, v228, v74
	v_fma_f32 v146, -v175, v229, v75
	s_waitcnt lgkmcnt(2)
	v_fma_f32 v136, -v175, v230, v76
	s_waitcnt lgkmcnt(0)
	v_fma_f32 v212, -v175, v226, v0
	v_fmac_f32_e32 v142, v212, v212
	ds_bpermute_b32 v144, v183, v142
	v_fma_f32 v128, -v175, v231, v77
	v_fma_f32 v119, -v175, v232, v95
	v_fma_f32 v112, -v175, v233, v79
	ds_read2st64_b32 v[228:229], v78 offset0:50 offset1:51
	ds_read2st64_b32 v[230:231], v78 offset0:52 offset1:53
	ds_read2st64_b32 v[232:233], v78 offset0:54 offset1:55
	s_waitcnt lgkmcnt(3)
	v_add_f32_e32 v142, v142, v144
	ds_bpermute_b32 v144, v182, v142
	v_mul_f32_e32 v215, v199, v199
	v_fma_f32 v210, -v175, v227, v5
	ds_read2st64_b32 v[226:227], v78 offset0:56 offset1:57
	v_fmac_f32_e32 v215, v194, v194
	s_waitcnt lgkmcnt(1)
	v_add_f32_e32 v142, v142, v144
	ds_bpermute_b32 v144, v181, v142
	v_fma_f32 v207, -v175, v185, v7
	v_fma_f32 v208, -v175, v228, v8
	v_fma_f32 v206, -v175, v229, v12
	v_fma_f32 v204, -v175, v230, v16
	s_waitcnt lgkmcnt(0)
	v_add_f32_e32 v142, v142, v144
	ds_bpermute_b32 v144, v180, v142
	v_fma_f32 v203, -v175, v231, v20
	v_fma_f32 v200, -v175, v232, v21
	v_fma_f32 v196, -v175, v233, v23
	ds_read2st64_b32 v[228:229], v78 offset0:58 offset1:59
	ds_read2st64_b32 v[230:231], v78 offset0:60 offset1:61
	ds_read2st64_b32 v[232:233], v78 offset0:62 offset1:63
	s_waitcnt lgkmcnt(3)
	v_add_f32_e32 v142, v142, v144
	ds_bpermute_b32 v144, v169, v142
	v_fmac_f32_e32 v215, v207, v207
	v_fmac_f32_e32 v215, v210, v210
	s_waitcnt lgkmcnt(3)
	v_fma_f32 v170, -v175, v229, v27
	ds_bpermute_b32 v229, v183, v215
	s_waitcnt lgkmcnt(1)
	v_add_f32_e32 v142, v142, v144
	v_fmamk_f32 v142, v142, 0x3c000000, v177
	v_mul_f32_e32 v144, 0x4f800000, v142
	v_cmp_gt_f32_e32 vcc, s49, v142
	v_fma_f32 v197, -v175, v192, v19
	v_fma_f32 v192, -v175, v193, v66
	v_cndmask_b32_e32 v144, v142, v144, vcc
	v_fma_f32 v193, -v175, v226, v24
	v_sqrt_f32_e32 v226, v144
	v_fma_f32 v201, -v175, v189, v15
	v_fma_f32 v189, -v175, v227, v25
	s_waitcnt lgkmcnt(0)
	v_add_f32_e32 v215, v215, v229
	v_add_u32_e32 v227, -1, v226
	v_fma_f32 v185, -v175, v228, v26
	v_fma_f32 v228, -v227, v226, v144
	ds_bpermute_b32 v229, v182, v215
	v_cmp_ge_f32_e64 s[0:1], 0, v228
	v_add_u32_e32 v228, 1, v226
	v_mul_f32_e32 v216, v195, v195
	v_cndmask_b32_e64 v227, v226, v227, s[0:1]
	v_fma_f32 v226, -v228, v226, v144
	v_cmp_lt_f32_e64 s[0:1], 0, v226
	s_waitcnt lgkmcnt(0)
; __device__ __forceinline__ void attn_unit_pp(int b, int h, int qb, int par, const bf16_t* __restrict__ QBp, const bf16_t* __restrict__ KBp, const bf16_t* __restrict__ VBp, ...
;     ...
;     for (int r = 0; r < 16; ++r) { float s = ss[r];
; #pragma unroll
;       for (int x = 1; x < 32; x <<= 1) s += __builtin_bit_cast(float, __builtin_amdgcn_ds_bpermute((lane ^ x) << 2, __builtin_bit_cast(int, s)));
;       ss[r] = 1.0f / sqrtf(s * (1.0f / 128.0f) + 1e-5f); }
	v_add_f32_e32 v215, v215, v229
	v_fmac_f32_e32 v216, v190, v190
	v_cndmask_b32_e64 v226, v227, v228, s[0:1]
	v_mul_f32_e32 v227, 0x37800000, v226
	v_cndmask_b32_e32 v226, v226, v227, vcc
	ds_bpermute_b32 v227, v181, v215
	v_cmp_class_f32_e32 vcc, v144, v176
	v_fmac_f32_e32 v216, v205, v205
	v_fmac_f32_e32 v216, v208, v208
	v_cndmask_b32_e32 v226, v226, v144, vcc
	s_waitcnt lgkmcnt(0)
	v_add_f32_e32 v215, v215, v227
	ds_bpermute_b32 v227, v180, v215
	v_div_scale_f32 v228, s[0:1], v226, v226, 1.0
	v_rcp_f32_e32 v229, v228
	v_fma_f32 v160, -v175, v230, v28
	s_waitcnt lgkmcnt(0)
	v_add_f32_e32 v215, v215, v227
	ds_bpermute_b32 v227, v169, v215
	v_fma_f32 v144, -v175, v233, v31
	v_fma_f32 v230, -v228, v229, 1.0
	ds_bpermute_b32 v233, v183, v216
	v_fmac_f32_e32 v229, v230, v229
	s_waitcnt lgkmcnt(1)
	v_add_f32_e32 v215, v215, v227
	v_fmamk_f32 v215, v215, 0x3c000000, v177
	v_mul_f32_e32 v227, 0x4f800000, v215
	v_cmp_gt_f32_e64 s[0:1], s49, v215
	v_div_scale_f32 v230, vcc, 1.0, v226, 1.0
	s_nop 0
	v_cndmask_b32_e64 v215, v215, v227, s[0:1]
	v_sqrt_f32_e32 v227, v215
	v_fma_f32 v153, -v175, v231, v29
	v_mul_f32_e32 v231, v230, v229
	v_fma_f32 v142, -v175, v232, v30
	v_fma_f32 v232, -v228, v231, v230
	v_fmac_f32_e32 v231, v232, v229
	v_fma_f32 v228, -v228, v231, v230
	v_add_u32_e32 v230, -1, v227
	s_waitcnt lgkmcnt(0)
	v_add_f32_e32 v216, v216, v233
	v_fma_f32 v232, -v230, v227, v215
	ds_bpermute_b32 v233, v182, v216
	v_cmp_ge_f32_e64 s[2:3], 0, v232
	v_add_u32_e32 v232, 1, v227
	v_mul_f32_e32 v218, v191, v191
	v_cndmask_b32_e64 v230, v227, v230, s[2:3]
	v_fma_f32 v227, -v232, v227, v215
	v_cmp_lt_f32_e64 s[2:3], 0, v227
	s_waitcnt lgkmcnt(0)
	v_add_f32_e32 v216, v216, v233
	v_fmac_f32_e32 v218, v186, v186
	v_cndmask_b32_e64 v227, v230, v232, s[2:3]
	v_mul_f32_e32 v230, 0x37800000, v227
	v_cndmask_b32_e64 v227, v227, v230, s[0:1]
	ds_bpermute_b32 v230, v181, v216
	v_cmp_class_f32_e64 s[0:1], v215, v176
	v_fmac_f32_e32 v218, v201, v201
	v_fmac_f32_e32 v218, v206, v206
	v_cndmask_b32_e64 v227, v227, v215, s[0:1]
	s_waitcnt lgkmcnt(0)
	v_add_f32_e32 v216, v216, v230
	ds_bpermute_b32 v230, v180, v216
	v_div_scale_f32 v232, s[0:1], v227, v227, 1.0
	v_rcp_f32_e32 v233, v232
	v_div_fmas_f32 v215, v228, v229, v231
	s_waitcnt lgkmcnt(0)
	v_add_f32_e32 v216, v216, v230
	ds_bpermute_b32 v228, v169, v216
	v_div_fixup_f32 v215, v215, v226, 1.0
	v_fma_f32 v226, -v232, v233, 1.0
	v_fmac_f32_e32 v233, v226, v233
	v_div_scale_f32 v226, vcc, 1.0, v227, 1.0
	v_mul_f32_e32 v229, v226, v233
	s_waitcnt lgkmcnt(0)
	v_add_f32_e32 v216, v216, v228
	v_fmamk_f32 v216, v216, 0x3c000000, v177
	v_fma_f32 v230, -v232, v229, v226
	v_mul_f32_e32 v228, 0x4f800000, v216
	v_cmp_gt_f32_e64 s[0:1], s49, v216
	v_fmac_f32_e32 v229, v230, v233
	v_fma_f32 v226, -v232, v229, v226
	v_cndmask_b32_e64 v216, v216, v228, s[0:1]
	ds_bpermute_b32 v232, v183, v218
	v_sqrt_f32_e32 v228, v216
	v_mul_f32_e32 v234, v187, v187
	v_fmac_f32_e32 v234, v171, v171
	v_fmac_f32_e32 v234, v197, v197
	v_add_u32_e32 v230, -1, v228
	s_waitcnt lgkmcnt(0)
	v_add_f32_e32 v218, v218, v232
	v_fma_f32 v231, -v230, v228, v216
	ds_bpermute_b32 v232, v182, v218
	v_cmp_ge_f32_e64 s[2:3], 0, v231
	v_add_u32_e32 v231, 1, v228
	v_fmac_f32_e32 v234, v204, v204
	v_cndmask_b32_e64 v230, v228, v230, s[2:3]
	v_fma_f32 v228, -v231, v228, v216
	v_cmp_lt_f32_e64 s[2:3], 0, v228
	s_waitcnt lgkmcnt(0)
	v_add_f32_e32 v218, v218, v232
	v_mul_f32_e32 v219, v172, v172
	v_cndmask_b32_e64 v228, v230, v231, s[2:3]
	v_mul_f32_e32 v230, 0x37800000, v228
	v_cndmask_b32_e64 v228, v228, v230, s[0:1]
	ds_bpermute_b32 v230, v181, v218
	v_cmp_class_f32_e64 s[0:1], v216, v176
	v_fmac_f32_e32 v219, v161, v161
	v_fmac_f32_e32 v219, v192, v192
	v_cndmask_b32_e64 v228, v228, v216, s[0:1]
	s_waitcnt lgkmcnt(0)
	v_add_f32_e32 v218, v218, v230
	ds_bpermute_b32 v230, v180, v218
	v_div_fmas_f32 v216, v226, v233, v229
	v_div_fixup_f32 v216, v216, v227, 1.0
	v_div_scale_f32 v231, s[0:1], v228, v228, 1.0
	s_waitcnt lgkmcnt(0)
	v_add_f32_e32 v218, v218, v230
	ds_bpermute_b32 v227, v169, v218
	v_rcp_f32_e32 v232, v231
	ds_bpermute_b32 v233, v183, v234
	v_fmac_f32_e32 v219, v203, v203
	v_mul_f32_e32 v221, v167, v167
	s_waitcnt lgkmcnt(1)
	v_add_f32_e32 v218, v218, v227
	v_fmamk_f32 v218, v218, 0x3c000000, v177
	v_mul_f32_e32 v227, 0x4f800000, v218
	v_cmp_gt_f32_e64 s[0:1], s49, v218
	v_fma_f32 v226, -v231, v232, 1.0
	v_fmac_f32_e32 v232, v226, v232
	v_cndmask_b32_e64 v218, v218, v227, s[0:1]
	v_sqrt_f32_e32 v227, v218
	v_div_scale_f32 v226, vcc, 1.0, v228, 1.0
	v_mul_f32_e32 v229, v226, v232
	v_fma_f32 v230, -v231, v229, v226
	v_fmac_f32_e32 v229, v230, v232
	v_add_u32_e32 v230, -1, v227
	v_fma_f32 v226, -v231, v229, v226
	v_fma_f32 v231, -v230, v227, v218
	s_waitcnt lgkmcnt(0)
	v_add_f32_e32 v233, v234, v233
	v_cmp_ge_f32_e64 s[2:3], 0, v231
	v_add_u32_e32 v231, 1, v227
	ds_bpermute_b32 v234, v182, v233
	v_cndmask_b32_e64 v230, v227, v230, s[2:3]
	v_fma_f32 v227, -v231, v227, v218
	v_cmp_lt_f32_e64 s[2:3], 0, v227
	v_fmac_f32_e32 v221, v150, v150
	v_fmac_f32_e32 v221, v188, v188
	v_cndmask_b32_e64 v227, v230, v231, s[2:3]
	v_mul_f32_e32 v230, 0x37800000, v227
	v_cndmask_b32_e64 v227, v227, v230, s[0:1]
	s_waitcnt lgkmcnt(0)
	v_add_f32_e32 v230, v233, v234
	ds_bpermute_b32 v231, v181, v230
	v_cmp_class_f32_e64 s[0:1], v218, v176
	v_fmac_f32_e32 v221, v200, v200
	v_mul_f32_e32 v222, v158, v158
	v_cndmask_b32_e64 v227, v227, v218, s[0:1]
	s_waitcnt lgkmcnt(0)
	v_add_f32_e32 v230, v230, v231
	ds_bpermute_b32 v231, v180, v230
	v_div_scale_f32 v233, s[0:1], v227, v227, 1.0
	v_div_fmas_f32 v218, v226, v232, v229
	v_rcp_f32_e32 v234, v233
	v_div_fixup_f32 v218, v218, v228, 1.0
	s_waitcnt lgkmcnt(0)
; __device__ __forceinline__ void attn_unit_pp(int b, int h, int qb, int par, const bf16_t* __restrict__ QBp, const bf16_t* __restrict__ KBp, const bf16_t* __restrict__ VBp, ...
;     ...
;     for (int r = 0; r < 16; ++r) { float s = ss[r];
; #pragma unroll
;       for (int x = 1; x < 32; x <<= 1) s += __builtin_bit_cast(float, __builtin_amdgcn_ds_bpermute((lane ^ x) << 2, __builtin_bit_cast(int, s)));
;       ss[r] = 1.0f / sqrtf(s * (1.0f / 128.0f) + 1e-5f); }
	v_add_f32_e32 v228, v230, v231
	ds_bpermute_b32 v229, v169, v228
	v_fma_f32 v226, -v233, v234, 1.0
	v_fmac_f32_e32 v234, v226, v234
	v_div_scale_f32 v226, vcc, 1.0, v227, 1.0
	v_mul_f32_e32 v230, v226, v234
	s_waitcnt lgkmcnt(0)
	v_add_f32_e32 v228, v228, v229
	v_fmamk_f32 v228, v228, 0x3c000000, v177
	v_fma_f32 v231, -v233, v230, v226
	v_mul_f32_e32 v229, 0x4f800000, v228
	v_cmp_gt_f32_e64 s[0:1], s49, v228
	v_fmac_f32_e32 v230, v231, v234
	v_fma_f32 v226, -v233, v230, v226
	v_cndmask_b32_e64 v228, v228, v229, s[0:1]
	ds_bpermute_b32 v233, v183, v219
	v_sqrt_f32_e32 v229, v228
	v_fmac_f32_e32 v222, v140, v140
	v_fmac_f32_e32 v222, v184, v184
	v_fmac_f32_e32 v222, v196, v196
	v_add_u32_e32 v231, -1, v229
	s_waitcnt lgkmcnt(0)
	v_add_f32_e32 v219, v219, v233
	v_fma_f32 v232, -v231, v229, v228
	ds_bpermute_b32 v233, v182, v219
	v_cmp_ge_f32_e64 s[2:3], 0, v232
	v_add_u32_e32 v232, 1, v229
	v_mul_f32_e32 v223, v155, v155
	v_cndmask_b32_e64 v231, v229, v231, s[2:3]
	v_fma_f32 v229, -v232, v229, v228
	v_cmp_lt_f32_e64 s[2:3], 0, v229
	s_waitcnt lgkmcnt(0)
	v_add_f32_e32 v219, v219, v233
	v_fmac_f32_e32 v223, v132, v132
	v_cndmask_b32_e64 v229, v231, v232, s[2:3]
	v_mul_f32_e32 v231, 0x37800000, v229
	v_cndmask_b32_e64 v229, v229, v231, s[0:1]
	ds_bpermute_b32 v231, v181, v219
	v_cmp_class_f32_e64 s[0:1], v228, v176
	v_fmac_f32_e32 v223, v173, v173
	v_fmac_f32_e32 v223, v193, v193
	v_cndmask_b32_e64 v228, v229, v228, s[0:1]
	s_waitcnt lgkmcnt(0)
	v_add_f32_e32 v231, v219, v231
	ds_bpermute_b32 v233, v180, v231
	v_div_fmas_f32 v219, v226, v234, v230
	v_div_fixup_f32 v219, v219, v227, 1.0
	v_div_scale_f32 v229, s[0:1], v228, v228, 1.0
	s_waitcnt lgkmcnt(0)
	v_add_f32_e32 v227, v231, v233
	ds_bpermute_b32 v230, v169, v227
	v_rcp_f32_e32 v232, v229
	ds_bpermute_b32 v234, v183, v221
	v_mul_f32_e32 v225, v145, v145
	v_fmac_f32_e32 v225, v125, v125
	s_waitcnt lgkmcnt(1)
	v_add_f32_e32 v227, v227, v230
	v_fmamk_f32 v227, v227, 0x3c000000, v177
	v_mul_f32_e32 v230, 0x4f800000, v227
	v_cmp_gt_f32_e64 s[0:1], s49, v227
	v_fma_f32 v226, -v229, v232, 1.0
	v_fmac_f32_e32 v232, v226, v232
	v_cndmask_b32_e64 v227, v227, v230, s[0:1]
	v_div_scale_f32 v226, vcc, 1.0, v228, 1.0
	v_sqrt_f32_e32 v230, v227
	v_mul_f32_e32 v231, v226, v232
	v_fma_f32 v233, -v229, v231, v226
	v_fmac_f32_e32 v231, v233, v232
	v_fma_f32 v226, -v229, v231, v226
	v_add_u32_e32 v229, -1, v230
	s_waitcnt lgkmcnt(0)
	v_add_f32_e32 v221, v221, v234
	v_fma_f32 v233, -v229, v230, v227
	ds_bpermute_b32 v234, v182, v221
	v_cmp_ge_f32_e64 s[2:3], 0, v233
	v_add_u32_e32 v233, 1, v230
	v_fmac_f32_e32 v225, v164, v164
	v_cndmask_b32_e64 v229, v230, v229, s[2:3]
	v_fma_f32 v230, -v233, v230, v227
	v_cmp_lt_f32_e64 s[2:3], 0, v230
	s_waitcnt lgkmcnt(0)
	v_add_f32_e32 v221, v221, v234
	v_fmac_f32_e32 v225, v189, v189
	v_cndmask_b32_e64 v229, v229, v233, s[2:3]
	v_mul_f32_e32 v230, 0x37800000, v229
	v_cndmask_b32_e64 v229, v229, v230, s[0:1]
	ds_bpermute_b32 v230, v181, v221
	v_cmp_class_f32_e64 s[0:1], v227, v176
	v_mul_f32_e32 v224, v135, v135
	v_fmac_f32_e32 v224, v116, v116
	v_cndmask_b32_e64 v227, v229, v227, s[0:1]
	s_waitcnt lgkmcnt(0)
	v_add_f32_e32 v230, v221, v230
	ds_bpermute_b32 v234, v180, v230
	v_div_fmas_f32 v221, v226, v232, v231
	v_div_fixup_f32 v221, v221, v228, 1.0
	v_div_scale_f32 v229, s[0:1], v227, v227, 1.0
	s_waitcnt lgkmcnt(0)
	v_add_f32_e32 v228, v230, v234
	ds_bpermute_b32 v230, v169, v228
	v_rcp_f32_e32 v233, v229
	ds_bpermute_b32 v234, v183, v222
	v_fmac_f32_e32 v224, v156, v156
	v_fmac_f32_e32 v224, v185, v185
	s_waitcnt lgkmcnt(1)
	v_add_f32_e32 v228, v228, v230
	v_fmamk_f32 v228, v228, 0x3c000000, v177
	v_mul_f32_e32 v230, 0x4f800000, v228
	v_cmp_gt_f32_e64 s[0:1], s49, v228
	v_fma_f32 v226, -v229, v233, 1.0
	v_fmac_f32_e32 v233, v226, v233
	v_cndmask_b32_e64 v228, v228, v230, s[0:1]
	v_div_scale_f32 v226, vcc, 1.0, v227, 1.0
	v_sqrt_f32_e32 v230, v228
	v_mul_f32_e32 v231, v226, v233
	v_fma_f32 v232, -v229, v231, v226
	v_fmac_f32_e32 v231, v232, v233
	v_fma_f32 v226, -v229, v231, v226
	v_add_u32_e32 v229, -1, v230
	s_waitcnt lgkmcnt(0)
	v_add_f32_e32 v222, v222, v234
	v_fma_f32 v232, -v229, v230, v228
	ds_bpermute_b32 v234, v182, v222
	v_cmp_ge_f32_e64 s[2:3], 0, v232
	v_add_u32_e32 v232, 1, v230
	v_mul_f32_e32 v220, v127, v127
	v_cndmask_b32_e64 v229, v230, v229, s[2:3]
	v_fma_f32 v230, -v232, v230, v228
	v_cmp_lt_f32_e64 s[2:3], 0, v230
	s_waitcnt lgkmcnt(0)
	v_add_f32_e32 v222, v222, v234
	v_fmac_f32_e32 v220, v107, v107
	v_cndmask_b32_e64 v229, v229, v232, s[2:3]
	v_mul_f32_e32 v230, 0x37800000, v229
	v_cndmask_b32_e64 v229, v229, v230, s[0:1]
	ds_bpermute_b32 v230, v181, v222
	v_cmp_class_f32_e64 s[0:1], v228, v176
	v_fmac_f32_e32 v220, v146, v146
	v_fmac_f32_e32 v220, v170, v170
	v_cndmask_b32_e64 v228, v229, v228, s[0:1]
	s_waitcnt lgkmcnt(0)
	v_add_f32_e32 v230, v222, v230
	ds_bpermute_b32 v234, v180, v230
	v_div_fmas_f32 v222, v226, v233, v231
	v_div_fixup_f32 v222, v222, v227, 1.0
	v_div_scale_f32 v229, s[0:1], v228, v228, 1.0
	s_waitcnt lgkmcnt(0)
	v_add_f32_e32 v227, v230, v234
	ds_bpermute_b32 v230, v169, v227
	v_rcp_f32_e32 v232, v229
	ds_bpermute_b32 v234, v183, v223
	v_mul_f32_e32 v217, v118, v118
	v_fmac_f32_e32 v217, v101, v101
	s_waitcnt lgkmcnt(1)
	v_add_f32_e32 v227, v227, v230
	v_fmamk_f32 v227, v227, 0x3c000000, v177
	v_mul_f32_e32 v230, 0x4f800000, v227
	v_cmp_gt_f32_e64 s[0:1], s49, v227
	v_fma_f32 v226, -v229, v232, 1.0
	v_fmac_f32_e32 v232, v226, v232
	v_cndmask_b32_e64 v227, v227, v230, s[0:1]
	v_div_scale_f32 v226, vcc, 1.0, v228, 1.0
	v_sqrt_f32_e32 v230, v227
	v_mul_f32_e32 v231, v226, v232
	v_fma_f32 v233, -v229, v231, v226
	v_fmac_f32_e32 v231, v233, v232
	v_fma_f32 v226, -v229, v231, v226
	v_add_u32_e32 v229, -1, v230
	s_waitcnt lgkmcnt(0)
; __device__ __forceinline__ float sigm_(float x) { return __builtin_amdgcn_rcpf(1.0f + __builtin_amdgcn_exp2f(-1.4426950408889634f * x)); }
; __device__ __forceinline__ void attn_unit_pp(int b, int h, int qb, int par, const bf16_t* __restrict__ QBp, const bf16_t* __restrict__ KBp, const bf16_t* __restrict__ VBp, ...
;     ...
;     for (int r = 0; r < 16; ++r) { float s = ss[r];
; #pragma unroll
;       for (int x = 1; x < 32; x <<= 1) s += __builtin_bit_cast(float, __builtin_amdgcn_ds_bpermute((lane ^ x) << 2, __builtin_bit_cast(int, s)));
;       ss[r] = 1.0f / sqrtf(s * (1.0f / 128.0f) + 1e-5f); }
;     float sg[4];
; #pragma unroll
;     for (int d0 = 0; d0 < 4; ++d0) sg[d0] = sub_g[d0 * 32 + r32] * 0.8f;
; #pragma unroll
;     for (int r = 0; r < 16; ++r)
; #pragma unroll
;       for (int d0 = 0; d0 < 4; ++d0) { const float ga = __uint_as_float(gate16[r * 4 + d0] << 16); o[d0][r] = o[d0][r] * ss[r] * sg[d0] * sigm_(ga); }
	v_add_f32_e32 v223, v223, v234
	v_fma_f32 v233, -v229, v230, v227
	ds_bpermute_b32 v234, v182, v223
	v_cmp_ge_f32_e64 s[2:3], 0, v233
	v_add_u32_e32 v233, 1, v230
	v_fmac_f32_e32 v217, v136, v136
	v_cndmask_b32_e64 v229, v230, v229, s[2:3]
	v_fma_f32 v230, -v233, v230, v227
	v_cmp_lt_f32_e64 s[2:3], 0, v230
	s_waitcnt lgkmcnt(0)
	v_add_f32_e32 v223, v223, v234
	v_fmac_f32_e32 v217, v160, v160
	v_cndmask_b32_e64 v229, v229, v233, s[2:3]
	v_mul_f32_e32 v230, 0x37800000, v229
	v_cndmask_b32_e64 v229, v229, v230, s[0:1]
	ds_bpermute_b32 v230, v181, v223
	v_cmp_class_f32_e64 s[0:1], v227, v176
	v_mul_f32_e32 v214, v111, v111
	v_fmac_f32_e32 v214, v58, v58
	v_cndmask_b32_e64 v227, v229, v227, s[0:1]
	s_waitcnt lgkmcnt(0)
	v_add_f32_e32 v230, v223, v230
	ds_bpermute_b32 v234, v180, v230
	v_div_fmas_f32 v223, v226, v232, v231
	v_div_fixup_f32 v223, v223, v228, 1.0
	v_div_scale_f32 v229, s[0:1], v227, v227, 1.0
	s_waitcnt lgkmcnt(0)
	v_add_f32_e32 v228, v230, v234
	ds_bpermute_b32 v230, v169, v228
	v_rcp_f32_e32 v233, v229
	ds_bpermute_b32 v234, v183, v225
	v_fmac_f32_e32 v214, v128, v128
	v_fmac_f32_e32 v214, v153, v153
	s_waitcnt lgkmcnt(1)
	v_add_f32_e32 v228, v228, v230
	v_fmamk_f32 v228, v228, 0x3c000000, v177
	v_mul_f32_e32 v230, 0x4f800000, v228
	v_cmp_gt_f32_e64 s[0:1], s49, v228
	v_fma_f32 v226, -v229, v233, 1.0
	v_fmac_f32_e32 v233, v226, v233
	v_cndmask_b32_e64 v228, v228, v230, s[0:1]
	v_div_scale_f32 v226, vcc, 1.0, v227, 1.0
	v_sqrt_f32_e32 v230, v228
	v_mul_f32_e32 v231, v226, v233
	v_fma_f32 v232, -v229, v231, v226
	v_fmac_f32_e32 v231, v232, v233
	v_fma_f32 v226, -v229, v231, v226
	v_add_u32_e32 v229, -1, v230
	s_waitcnt lgkmcnt(0)
	v_add_f32_e32 v225, v225, v234
	v_fma_f32 v232, -v229, v230, v228
	ds_bpermute_b32 v234, v182, v225
	v_cmp_ge_f32_e64 s[2:3], 0, v232
	v_add_u32_e32 v232, 1, v230
	v_mul_f32_e32 v213, v103, v103
	v_cndmask_b32_e64 v229, v230, v229, s[2:3]
	v_fma_f32 v230, -v232, v230, v228
	v_cmp_lt_f32_e64 s[2:3], 0, v230
	s_waitcnt lgkmcnt(0)
	v_add_f32_e32 v225, v225, v234
	v_fmac_f32_e32 v213, v51, v51
	v_cndmask_b32_e64 v229, v229, v232, s[2:3]
	v_mul_f32_e32 v230, 0x37800000, v229
	v_cndmask_b32_e64 v229, v229, v230, s[0:1]
	ds_bpermute_b32 v230, v181, v225
	v_cmp_class_f32_e64 s[0:1], v228, v176
	v_fmac_f32_e32 v213, v119, v119
	v_fmac_f32_e32 v213, v142, v142
	v_cndmask_b32_e64 v228, v229, v228, s[0:1]
	s_waitcnt lgkmcnt(0)
	v_add_f32_e32 v230, v225, v230
	ds_bpermute_b32 v234, v180, v230
	v_div_fmas_f32 v225, v226, v233, v231
	v_div_fixup_f32 v225, v225, v227, 1.0
	v_div_scale_f32 v229, s[0:1], v228, v228, 1.0
	s_waitcnt lgkmcnt(0)
	v_add_f32_e32 v227, v230, v234
	ds_bpermute_b32 v230, v169, v227
	v_rcp_f32_e32 v232, v229
	ds_bpermute_b32 v234, v183, v224
	v_mul_f32_e32 v211, v61, v61
	v_fmac_f32_e32 v211, v46, v46
	s_waitcnt lgkmcnt(1)
	v_add_f32_e32 v227, v227, v230
	v_fmamk_f32 v227, v227, 0x3c000000, v177
	v_mul_f32_e32 v230, 0x4f800000, v227
	v_cmp_gt_f32_e64 s[0:1], s49, v227
	v_fma_f32 v226, -v229, v232, 1.0
	v_fmac_f32_e32 v232, v226, v232
	v_cndmask_b32_e64 v227, v227, v230, s[0:1]
	v_div_scale_f32 v226, vcc, 1.0, v228, 1.0
	v_sqrt_f32_e32 v230, v227
	v_mul_f32_e32 v231, v226, v232
	v_fma_f32 v233, -v229, v231, v226
	v_fmac_f32_e32 v231, v233, v232
	v_fma_f32 v226, -v229, v231, v226
	v_add_u32_e32 v229, -1, v230
	s_waitcnt lgkmcnt(0)
	v_add_f32_e32 v224, v224, v234
	v_fma_f32 v233, -v229, v230, v227
	ds_bpermute_b32 v234, v182, v224
	v_cmp_ge_f32_e64 s[2:3], 0, v233
	v_add_u32_e32 v233, 1, v230
	v_fmac_f32_e32 v211, v112, v112
	v_cndmask_b32_e64 v229, v230, v229, s[2:3]
	v_fma_f32 v230, -v233, v230, v227
	v_cmp_lt_f32_e64 s[2:3], 0, v230
	s_waitcnt lgkmcnt(0)
	v_add_f32_e32 v224, v224, v234
	v_fmac_f32_e32 v211, v144, v144
	v_cndmask_b32_e64 v229, v229, v233, s[2:3]
	v_mul_f32_e32 v230, 0x37800000, v229
	v_cndmask_b32_e64 v229, v229, v230, s[0:1]
	ds_bpermute_b32 v230, v181, v224
	v_cmp_class_f32_e64 s[0:1], v227, v176
	s_waitcnt vmcnt(61)
	v_lshlrev_b32_e32 v162, 16, v162
	v_exp_f32_e32 v163, v163
	v_cndmask_b32_e64 v227, v229, v227, s[0:1]
	s_waitcnt lgkmcnt(0)
	v_add_f32_e32 v230, v224, v230
	ds_bpermute_b32 v234, v180, v230
	v_div_fmas_f32 v224, v226, v232, v231
	v_div_fixup_f32 v224, v224, v228, 1.0
	v_div_scale_f32 v229, s[0:1], v227, v227, 1.0
	s_waitcnt lgkmcnt(0)
	v_add_f32_e32 v228, v230, v234
	ds_bpermute_b32 v230, v169, v228
	v_rcp_f32_e32 v233, v229
	ds_bpermute_b32 v234, v183, v220
	v_mul_f32_e32 v162, 0xbfb8aa3b, v162
	s_waitcnt vmcnt(60)
	v_lshlrev_b32_e32 v159, 16, v159
	s_waitcnt lgkmcnt(1)
	v_add_f32_e32 v228, v228, v230
	v_fmamk_f32 v228, v228, 0x3c000000, v177
	v_mul_f32_e32 v230, 0x4f800000, v228
	v_cmp_gt_f32_e64 s[0:1], s49, v228
	v_fma_f32 v226, -v229, v233, 1.0
	v_fmac_f32_e32 v233, v226, v233
	v_cndmask_b32_e64 v228, v228, v230, s[0:1]
	v_div_scale_f32 v226, vcc, 1.0, v227, 1.0
	v_sqrt_f32_e32 v230, v228
	v_mul_f32_e32 v231, v226, v233
	v_fma_f32 v232, -v229, v231, v226
	v_fmac_f32_e32 v231, v232, v233
	v_fma_f32 v226, -v229, v231, v226
	v_add_u32_e32 v229, -1, v230
	s_waitcnt lgkmcnt(0)
	v_add_f32_e32 v220, v220, v234
	v_fma_f32 v232, -v229, v230, v228
	ds_bpermute_b32 v234, v182, v220
	v_cmp_ge_f32_e64 s[2:3], 0, v232
	v_add_u32_e32 v232, 1, v230
	v_add_f32_e32 v163, 1.0, v163
	v_cndmask_b32_e64 v229, v230, v229, s[2:3]
	v_fma_f32 v230, -v232, v230, v228
	v_cmp_lt_f32_e64 s[2:3], 0, v230
	s_waitcnt lgkmcnt(0)
	v_add_f32_e32 v220, v220, v234
	v_mul_f32_e32 v159, 0xbfb8aa3b, v159
	v_cndmask_b32_e64 v229, v229, v232, s[2:3]
	v_mul_f32_e32 v230, 0x37800000, v229
	v_cndmask_b32_e64 v229, v229, v230, s[0:1]
	ds_bpermute_b32 v230, v181, v220
	v_cmp_class_f32_e64 s[0:1], v228, v176
	s_waitcnt vmcnt(58)
; __device__ __forceinline__ float sigm_(float x) { return __builtin_amdgcn_rcpf(1.0f + __builtin_amdgcn_exp2f(-1.4426950408889634f * x)); }
; __device__ __forceinline__ void attn_unit_pp(int b, int h, int qb, int par, const bf16_t* __restrict__ QBp, const bf16_t* __restrict__ KBp, const bf16_t* __restrict__ VBp, ...
;     ...
;     for (int r = 0; r < 16; ++r) { float s = ss[r];
; #pragma unroll
;       for (int x = 1; x < 32; x <<= 1) s += __builtin_bit_cast(float, __builtin_amdgcn_ds_bpermute((lane ^ x) << 2, __builtin_bit_cast(int, s)));
;       ss[r] = 1.0f / sqrtf(s * (1.0f / 128.0f) + 1e-5f); }
;     float sg[4];
; #pragma unroll
;     for (int d0 = 0; d0 < 4; ++d0) sg[d0] = sub_g[d0 * 32 + r32] * 0.8f;
; #pragma unroll
;     for (int r = 0; r < 16; ++r)
; #pragma unroll
;       for (int d0 = 0; d0 < 4; ++d0) { const float ga = __uint_as_float(gate16[r * 4 + d0] << 16); o[d0][r] = o[d0][r] * ss[r] * sg[d0] * sigm_(ga); }
	v_lshlrev_b32_e32 v154, 16, v154
	v_lshlrev_b32_e32 v157, 16, v157
	v_cndmask_b32_e64 v228, v229, v228, s[0:1]
	s_waitcnt lgkmcnt(0)
	v_add_f32_e32 v230, v220, v230
	ds_bpermute_b32 v234, v180, v230
	v_div_fmas_f32 v220, v226, v233, v231
	v_div_fixup_f32 v220, v220, v227, 1.0
	v_div_scale_f32 v229, s[0:1], v228, v228, 1.0
	s_waitcnt lgkmcnt(0)
	v_add_f32_e32 v227, v230, v234
	ds_bpermute_b32 v230, v169, v227
	v_rcp_f32_e32 v232, v229
	ds_bpermute_b32 v234, v183, v217
	v_mul_f32_e32 v154, 0xbfb8aa3b, v154
	s_waitcnt vmcnt(57)
	v_lshlrev_b32_e32 v152, 16, v152
	s_waitcnt lgkmcnt(1)
	v_add_f32_e32 v227, v227, v230
	v_fmamk_f32 v227, v227, 0x3c000000, v177
	v_mul_f32_e32 v230, 0x4f800000, v227
	v_cmp_gt_f32_e64 s[0:1], s49, v227
	v_fma_f32 v226, -v229, v232, 1.0
	v_fmac_f32_e32 v232, v226, v232
	v_cndmask_b32_e64 v227, v227, v230, s[0:1]
	v_div_scale_f32 v226, vcc, 1.0, v228, 1.0
	v_sqrt_f32_e32 v230, v227
	v_mul_f32_e32 v231, v226, v232
	v_fma_f32 v233, -v229, v231, v226
	v_fmac_f32_e32 v231, v233, v232
	v_fma_f32 v226, -v229, v231, v226
	v_add_u32_e32 v229, -1, v230
	s_waitcnt lgkmcnt(0)
	v_add_f32_e32 v217, v217, v234
	v_fma_f32 v233, -v229, v230, v227
	ds_bpermute_b32 v234, v182, v217
	v_cmp_ge_f32_e64 s[2:3], 0, v233
	v_add_u32_e32 v233, 1, v230
	v_mul_f32_e32 v157, 0xbfb8aa3b, v157
	v_cndmask_b32_e64 v229, v230, v229, s[2:3]
	v_fma_f32 v230, -v233, v230, v227
	v_cmp_lt_f32_e64 s[2:3], 0, v230
	s_waitcnt lgkmcnt(0)
	v_add_f32_e32 v217, v217, v234
	v_exp_f32_e32 v154, v154
	v_cndmask_b32_e64 v229, v229, v233, s[2:3]
	v_mul_f32_e32 v230, 0x37800000, v229
	v_cndmask_b32_e64 v229, v229, v230, s[0:1]
	ds_bpermute_b32 v230, v181, v217
	v_cmp_class_f32_e64 s[0:1], v227, v176
	v_mul_f32_e32 v152, 0xbfb8aa3b, v152
	s_waitcnt vmcnt(56)
	v_lshlrev_b32_e32 v149, 16, v149
	v_cndmask_b32_e64 v227, v229, v227, s[0:1]
	s_waitcnt lgkmcnt(0)
	v_add_f32_e32 v230, v217, v230
	ds_bpermute_b32 v234, v180, v230
	v_div_fmas_f32 v217, v226, v232, v231
	v_div_fixup_f32 v217, v217, v228, 1.0
	v_div_scale_f32 v229, s[0:1], v227, v227, 1.0
	s_waitcnt lgkmcnt(0)
	v_add_f32_e32 v228, v230, v234
	ds_bpermute_b32 v230, v169, v228
	v_rcp_f32_e32 v233, v229
	ds_bpermute_b32 v234, v183, v214
	v_add_f32_e32 v154, 1.0, v154
	v_mul_f32_e32 v149, 0xbfb8aa3b, v149
	s_waitcnt lgkmcnt(1)
	v_add_f32_e32 v228, v228, v230
	v_fmamk_f32 v228, v228, 0x3c000000, v177
	v_mul_f32_e32 v230, 0x4f800000, v228
	v_cmp_gt_f32_e64 s[0:1], s49, v228
	v_fma_f32 v226, -v229, v233, 1.0
	v_fmac_f32_e32 v233, v226, v233
	v_cndmask_b32_e64 v228, v228, v230, s[0:1]
	v_div_scale_f32 v226, vcc, 1.0, v227, 1.0
	v_sqrt_f32_e32 v230, v228
	v_mul_f32_e32 v231, v226, v233
	v_fma_f32 v232, -v229, v231, v226
	v_fmac_f32_e32 v231, v232, v233
	v_fma_f32 v226, -v229, v231, v226
	v_add_u32_e32 v229, -1, v230
	s_waitcnt lgkmcnt(0)
	v_add_f32_e32 v214, v214, v234
	v_fma_f32 v232, -v229, v230, v228
	ds_bpermute_b32 v234, v182, v214
	v_cmp_ge_f32_e64 s[2:3], 0, v232
	v_add_u32_e32 v232, 1, v230
	v_lshlrev_b32_e32 v165, 16, v165
	v_cndmask_b32_e64 v229, v230, v229, s[2:3]
	v_fma_f32 v230, -v232, v230, v228
	v_cmp_lt_f32_e64 s[2:3], 0, v230
	s_waitcnt lgkmcnt(0)
	v_add_f32_e32 v214, v214, v234
	v_mul_f32_e32 v165, 0xbfb8aa3b, v165
	v_cndmask_b32_e64 v229, v229, v232, s[2:3]
	v_mul_f32_e32 v230, 0x37800000, v229
	v_cndmask_b32_e64 v229, v229, v230, s[0:1]
	ds_bpermute_b32 v230, v181, v214
	v_cmp_class_f32_e64 s[0:1], v228, v176
	s_waitcnt vmcnt(55)
	v_lshlrev_b32_e32 v151, 16, v151
	s_waitcnt vmcnt(54)
	v_lshlrev_b32_e32 v148, 16, v148
	v_cndmask_b32_e64 v228, v229, v228, s[0:1]
	s_waitcnt lgkmcnt(0)
	v_add_f32_e32 v230, v214, v230
	ds_bpermute_b32 v234, v180, v230
	v_div_fmas_f32 v214, v226, v233, v231
	v_div_fixup_f32 v214, v214, v227, 1.0
	v_div_scale_f32 v229, s[0:1], v228, v228, 1.0
	s_waitcnt lgkmcnt(0)
	v_add_f32_e32 v227, v230, v234
	ds_bpermute_b32 v230, v169, v227
	v_rcp_f32_e32 v232, v229
	ds_bpermute_b32 v234, v183, v213
	ds_bpermute_b32 v183, v183, v211
	v_exp_f32_e32 v165, v165
	s_waitcnt lgkmcnt(2)
	v_add_f32_e32 v227, v227, v230
	v_fmamk_f32 v227, v227, 0x3c000000, v177
	v_mul_f32_e32 v230, 0x4f800000, v227
	v_cmp_gt_f32_e64 s[0:1], s49, v227
	v_fma_f32 v226, -v229, v232, 1.0
	v_fmac_f32_e32 v232, v226, v232
	v_cndmask_b32_e64 v227, v227, v230, s[0:1]
	v_div_scale_f32 v226, vcc, 1.0, v228, 1.0
	v_sqrt_f32_e32 v230, v227
	v_mul_f32_e32 v231, v226, v232
	v_fma_f32 v233, -v229, v231, v226
	v_fmac_f32_e32 v231, v233, v232
	v_fma_f32 v226, -v229, v231, v226
	v_add_u32_e32 v229, -1, v230
	s_waitcnt lgkmcnt(1)
	v_add_f32_e32 v213, v213, v234
	v_fma_f32 v233, -v229, v230, v227
	ds_bpermute_b32 v234, v182, v213
	v_cmp_ge_f32_e64 s[2:3], 0, v233
	v_add_u32_e32 v233, 1, v230
	s_waitcnt lgkmcnt(1)
	v_add_f32_e32 v183, v211, v183
	v_cndmask_b32_e64 v229, v230, v229, s[2:3]
	v_fma_f32 v230, -v233, v230, v227
	v_cmp_lt_f32_e64 s[2:3], 0, v230
	s_waitcnt lgkmcnt(0)
	v_add_f32_e32 v213, v213, v234
	ds_bpermute_b32 v182, v182, v183
	v_cndmask_b32_e64 v229, v229, v233, s[2:3]
	v_mul_f32_e32 v230, 0x37800000, v229
	v_cndmask_b32_e64 v229, v229, v230, s[0:1]
	ds_bpermute_b32 v230, v181, v213
	v_cmp_class_f32_e64 s[0:1], v227, v176
	s_waitcnt lgkmcnt(1)
	v_add_f32_e32 v182, v183, v182
	ds_bpermute_b32 v181, v181, v182
	v_cndmask_b32_e64 v227, v229, v227, s[0:1]
	s_waitcnt lgkmcnt(1)
	v_add_f32_e32 v230, v213, v230
	ds_bpermute_b32 v234, v180, v230
	v_div_fmas_f32 v213, v226, v232, v231
	v_lshlrev_b32_e32 v232, 2, v179
	v_div_fixup_f32 v213, v213, v228, 1.0
	v_div_scale_f32 v229, s[0:1], v227, v227, 1.0
	s_waitcnt lgkmcnt(0)
; __device__ __forceinline__ float sigm_(float x) { return __builtin_amdgcn_rcpf(1.0f + __builtin_amdgcn_exp2f(-1.4426950408889634f * x)); }
; __device__ __forceinline__ void attn_unit_pp(int b, int h, int qb, int par, const bf16_t* __restrict__ QBp, const bf16_t* __restrict__ KBp, const bf16_t* __restrict__ VBp, ...
;     ...
;       ss[r] = 1.0f / sqrtf(s * (1.0f / 128.0f) + 1e-5f); }
;     float sg[4];
; #pragma unroll
;     for (int d0 = 0; d0 < 4; ++d0) sg[d0] = sub_g[d0 * 32 + r32] * 0.8f;
; #pragma unroll
;     for (int r = 0; r < 16; ++r)
; #pragma unroll
;       for (int d0 = 0; d0 < 4; ++d0) { const float ga = __uint_as_float(gate16[r * 4 + d0] << 16); o[d0][r] = o[d0][r] * ss[r] * sg[d0] * sigm_(ga); }
	v_add_f32_e32 v228, v230, v234
	global_load_dword v234, v232, s[54:55]
	global_load_dword v235, v232, s[54:55] offset:128
	global_load_dword v236, v232, s[54:55] offset:256
	ds_bpermute_b32 v230, v169, v228
	v_rcp_f32_e32 v233, v229
	global_load_dword v237, v232, s[54:55] offset:384
	v_add_f32_e32 v181, v182, v181
	ds_bpermute_b32 v180, v180, v181
	s_waitcnt lgkmcnt(1)
	v_add_f32_e32 v228, v228, v230
	v_fmamk_f32 v228, v228, 0x3c000000, v177
	v_mul_f32_e32 v230, 0x4f800000, v228
	v_cmp_gt_f32_e64 s[0:1], s49, v228
	v_fma_f32 v226, -v229, v233, 1.0
	v_fmac_f32_e32 v233, v226, v233
	v_cndmask_b32_e64 v228, v228, v230, s[0:1]
	v_div_scale_f32 v226, vcc, 1.0, v227, 1.0
	v_sqrt_f32_e32 v230, v228
	v_mul_f32_e32 v231, v226, v233
	v_fma_f32 v232, -v229, v231, v226
	v_fmac_f32_e32 v231, v232, v233
	v_fma_f32 v226, -v229, v231, v226
	v_add_u32_e32 v229, -1, v230
	v_fma_f32 v232, -v229, v230, v228
	v_cmp_ge_f32_e64 s[2:3], 0, v232
	v_add_u32_e32 v232, 1, v230
	s_waitcnt lgkmcnt(0)
	v_add_f32_e32 v180, v181, v180
	v_cndmask_b32_e64 v229, v230, v229, s[2:3]
	v_fma_f32 v230, -v232, v230, v228
	v_cmp_lt_f32_e64 s[2:3], 0, v230
	ds_bpermute_b32 v169, v169, v180
	v_div_fmas_f32 v182, v226, v233, v231
	v_cndmask_b32_e64 v211, v229, v232, s[2:3]
	v_mul_f32_e32 v229, 0x37800000, v211
	v_cndmask_b32_e64 v211, v211, v229, s[0:1]
	v_cmp_class_f32_e64 s[0:1], v228, v176
	s_waitcnt lgkmcnt(0)
	v_add_f32_e32 v169, v180, v169
	v_fmamk_f32 v169, v169, 0x3c000000, v177
	v_cndmask_b32_e64 v183, v211, v228, s[0:1]
	v_div_scale_f32 v211, s[0:1], v183, v183, 1.0
	v_rcp_f32_e32 v228, v211
	v_mul_f32_e32 v180, 0x4f800000, v169
	v_cmp_gt_f32_e64 s[0:1], s49, v169
	v_div_fixup_f32 v232, v182, v227, 1.0
	v_fma_f32 v182, -v211, v228, 1.0
	v_cndmask_b32_e64 v169, v169, v180, s[0:1]
	v_fmac_f32_e32 v228, v182, v228
	v_div_scale_f32 v181, vcc, 1.0, v183, 1.0
	v_sqrt_f32_e32 v180, v169
	v_mul_f32_e32 v182, v181, v228
	v_fma_f32 v226, -v211, v182, v181
	v_fmac_f32_e32 v182, v226, v228
	v_fma_f32 v181, -v211, v182, v181
	v_add_u32_e32 v211, -1, v180
	v_fma_f32 v226, -v211, v180, v169
	v_cmp_ge_f32_e64 s[2:3], 0, v226
	v_add_u32_e32 v226, 1, v180
	v_div_fmas_f32 v181, v181, v228, v182
	v_cndmask_b32_e64 v211, v180, v211, s[2:3]
	v_fma_f32 v180, -v226, v180, v169
	v_cmp_lt_f32_e64 s[2:3], 0, v180
	v_div_fixup_f32 v230, v181, v183, 1.0
	v_mul_f32_e32 v151, 0xbfb8aa3b, v151
	v_cndmask_b32_e64 v180, v211, v226, s[2:3]
	v_mul_f32_e32 v211, 0x37800000, v180
	v_cndmask_b32_e64 v180, v180, v211, s[0:1]
	v_cmp_class_f32_e64 s[0:1], v169, v176
	v_mul_f32_e32 v148, 0xbfb8aa3b, v148
	s_waitcnt vmcnt(57)
	v_lshlrev_b32_e32 v147, 16, v147
	v_cndmask_b32_e64 v169, v180, v169, s[0:1]
	v_div_scale_f32 v180, s[0:1], v169, v169, 1.0
	v_rcp_f32_e32 v211, v180
	s_waitcnt vmcnt(55)
	v_lshlrev_b32_e32 v141, 16, v141
	v_exp_f32_e32 v148, v148
	v_mul_f32_e32 v147, 0xbfb8aa3b, v147
	v_fma_f32 v181, -v180, v211, 1.0
	v_fmac_f32_e32 v211, v181, v211
	v_div_scale_f32 v181, vcc, 1.0, v169, 1.0
	v_mul_f32_e32 v182, v181, v211
	v_fma_f32 v183, -v180, v182, v181
	v_fmac_f32_e32 v182, v183, v211
	v_fma_f32 v180, -v180, v182, v181
	v_div_fmas_f32 v180, v180, v211, v182
	v_div_fixup_f32 v226, v180, v169, 1.0
	v_exp_f32_e32 v180, v162
	s_waitcnt vmcnt(3)
	v_mul_f32_e32 v231, 0x3f4ccccd, v234
	v_mul_f32_e32 v169, v198, v215
	v_mul_f32_e32 v198, v169, v231
	v_rcp_f32_e32 v169, v163
	v_add_f32_e32 v163, 1.0, v180
	v_exp_f32_e32 v180, v159
	v_exp_f32_e32 v181, v157
	v_exp_f32_e32 v182, v152
	v_exp_f32_e32 v183, v151
	v_add_f32_e32 v180, 1.0, v180
	v_rcp_f32_e32 v157, v180
	v_mul_f32_e32 v180, v194, v216
	v_mul_f32_e32 v194, v180, v231
	v_add_f32_e32 v180, 1.0, v181
	v_rcp_f32_e32 v181, v154
	v_add_f32_e32 v154, 1.0, v182
	v_exp_f32_e32 v182, v149
	v_mul_f32_e32 v141, 0xbfb8aa3b, v141
	v_add_f32_e32 v165, 1.0, v165
	v_lshlrev_b32_e32 v143, 16, v143
	v_add_f32_e32 v182, 1.0, v182
	v_rcp_f32_e32 v151, v182
	v_mul_f32_e32 v182, v190, v218
	v_exp_f32_e32 v190, v147
	v_mul_f32_e32 v147, v205, v218
	v_exp_f32_e32 v205, v141
	v_lshlrev_b32_e32 v139, 16, v139
	v_rcp_f32_e32 v211, v165
	v_mul_f32_e32 v165, v202, v215
	v_rcp_f32_e32 v202, v180
	v_mul_f32_e32 v180, v199, v216
	v_mul_f32_e32 v199, v182, v231
	v_add_f32_e32 v182, 1.0, v183
	v_add_f32_e32 v148, 1.0, v148
	v_mul_f32_e32 v143, 0xbfb8aa3b, v143
	v_mul_f32_e32 v186, v186, v219
	v_mul_f32_e32 v139, 0xbfb8aa3b, v139
	v_lshlrev_b32_e32 v138, 16, v138
	v_mul_f32_e32 v152, v207, v216
	v_rcp_f32_e32 v207, v182
	v_mul_f32_e32 v182, v195, v218
	v_rcp_f32_e32 v183, v148
	v_add_f32_e32 v148, 1.0, v190
	v_exp_f32_e32 v190, v143
	v_mul_f32_e32 v195, v186, v231
	v_add_f32_e32 v186, 1.0, v205
	v_exp_f32_e32 v139, v139
	v_mul_f32_e32 v138, 0xbfb8aa3b, v138
	v_rcp_f32_e32 v205, v186
	v_mul_f32_e32 v186, v191, v219
	v_exp_f32_e32 v191, v138
	v_lshlrev_b32_e32 v134, 16, v134
	v_add_f32_e32 v190, 1.0, v190
	v_add_f32_e32 v139, 1.0, v139
	v_mul_f32_e32 v134, 0xbfb8aa3b, v134
	v_lshlrev_b32_e32 v137, 16, v137
	v_lshlrev_b32_e32 v133, 16, v133
	v_rcp_f32_e32 v141, v190
	v_rcp_f32_e32 v190, v139
	v_add_f32_e32 v139, 1.0, v191
	v_exp_f32_e32 v191, v134
	v_mul_f32_e32 v137, 0xbfb8aa3b, v137
	v_mul_f32_e32 v133, 0xbfb8aa3b, v133
	v_lshlrev_b32_e32 v131, 16, v131
	v_mul_f32_e32 v138, v201, v219
	v_exp_f32_e32 v201, v137
	v_exp_f32_e32 v133, v133
	v_mul_f32_e32 v131, 0xbfb8aa3b, v131
	v_mul_f32_e32 v134, v206, v219
	v_exp_f32_e32 v206, v131
	v_add_f32_e32 v191, 1.0, v191
	v_mul_f32_e32 v171, v171, v221
	v_lshlrev_b32_e32 v124, 16, v124
	v_lshlrev_b32_e32 v122, 16, v122
	v_rcp_f32_e32 v137, v191
	v_mul_f32_e32 v191, v171, v231
	v_add_f32_e32 v171, 1.0, v201
	v_add_f32_e32 v133, 1.0, v133
; __device__ __forceinline__ float sigm_(float x) { return __builtin_amdgcn_rcpf(1.0f + __builtin_amdgcn_exp2f(-1.4426950408889634f * x)); }
; __device__ __forceinline__ void attn_unit_pp(int b, int h, int qb, int par, const bf16_t* __restrict__ QBp, const bf16_t* __restrict__ KBp, const bf16_t* __restrict__ VBp, ...
;     ...
; #pragma unroll
;     for (int r = 0; r < 16; ++r)
; #pragma unroll
;       for (int d0 = 0; d0 < 4; ++d0) { const float ga = __uint_as_float(gate16[r * 4 + d0] << 16); o[d0][r] = o[d0][r] * ss[r] * sg[d0] * sigm_(ga); }
	v_mul_f32_e32 v124, 0xbfb8aa3b, v124
	v_mul_f32_e32 v122, 0xbfb8aa3b, v122
	v_rcp_f32_e32 v201, v171
	v_mul_f32_e32 v171, v187, v221
	v_rcp_f32_e32 v187, v133
	v_add_f32_e32 v133, 1.0, v206
	v_lshlrev_b32_e32 v130, 16, v130
	v_exp_f32_e32 v206, v124
	v_mul_f32_e32 v124, v192, v222
	v_exp_f32_e32 v192, v122
	v_mul_f32_e32 v130, 0xbfb8aa3b, v130
	v_lshlrev_b32_e32 v129, 16, v129
	v_lshlrev_b32_e32 v126, 16, v126
	v_mul_f32_e32 v131, v197, v221
	v_exp_f32_e32 v197, v130
	v_mul_f32_e32 v129, 0xbfb8aa3b, v129
	v_mul_f32_e32 v126, 0xbfb8aa3b, v126
	v_lshlrev_b32_e32 v123, 16, v123
	v_lshlrev_b32_e32 v121, 16, v121
	v_mul_f32_e32 v130, v204, v221
	v_exp_f32_e32 v204, v129
	v_exp_f32_e32 v126, v126
	v_mul_f32_e32 v123, 0xbfb8aa3b, v123
	v_mul_f32_e32 v121, 0xbfb8aa3b, v121
	v_lshlrev_b32_e32 v120, 16, v120
	v_lshlrev_b32_e32 v117, 16, v117
	v_mul_f32_e32 v122, v203, v222
	v_add_f32_e32 v192, 1.0, v192
	v_exp_f32_e32 v203, v123
	v_exp_f32_e32 v121, v121
	v_mul_f32_e32 v120, 0xbfb8aa3b, v120
	v_mul_f32_e32 v117, 0xbfb8aa3b, v117
	v_rcp_f32_e32 v123, v192
	v_exp_f32_e32 v192, v120
	v_mul_f32_e32 v120, v188, v223
	v_exp_f32_e32 v188, v117
	v_add_f32_e32 v197, 1.0, v197
	v_mul_f32_e32 v161, v161, v222
	v_rcp_f32_e32 v129, v197
	v_mul_f32_e32 v197, v161, v231
	v_add_f32_e32 v161, 1.0, v204
	v_add_f32_e32 v126, 1.0, v126
	v_mul_f32_e32 v150, v150, v223
	v_lshlrev_b32_e32 v115, 16, v115
	v_lshlrev_b32_e32 v114, 16, v114
	v_rcp_f32_e32 v204, v161
	v_mul_f32_e32 v161, v172, v222
	v_rcp_f32_e32 v172, v126
	v_add_f32_e32 v126, 1.0, v206
	v_mul_f32_e32 v206, v150, v231
	v_add_f32_e32 v150, 1.0, v203
	v_add_f32_e32 v121, 1.0, v121
	v_mul_f32_e32 v115, 0xbfb8aa3b, v115
	v_mul_f32_e32 v114, 0xbfb8aa3b, v114
	v_lshlrev_b32_e32 v113, 16, v113
	v_lshlrev_b32_e32 v109, 16, v109
	v_rcp_f32_e32 v203, v150
	v_mul_f32_e32 v150, v167, v223
	v_rcp_f32_e32 v167, v121
	v_add_f32_e32 v121, 1.0, v192
	v_add_f32_e32 v188, 1.0, v188
	v_exp_f32_e32 v192, v115
	v_exp_f32_e32 v114, v114
	v_mul_f32_e32 v113, 0xbfb8aa3b, v113
	v_mul_f32_e32 v109, 0xbfb8aa3b, v109
	v_rcp_f32_e32 v115, v188
	v_exp_f32_e32 v188, v113
	v_mul_f32_e32 v113, v184, v225
	v_exp_f32_e32 v184, v109
	v_mul_f32_e32 v140, v140, v225
	v_lshlrev_b32_e32 v110, 16, v110
	v_lshlrev_b32_e32 v108, 16, v108
	v_mul_f32_e32 v117, v200, v223
	v_mul_f32_e32 v200, v140, v231
	v_add_f32_e32 v140, 1.0, v192
	v_add_f32_e32 v114, 1.0, v114
	v_mul_f32_e32 v110, 0xbfb8aa3b, v110
	v_mul_f32_e32 v108, 0xbfb8aa3b, v108
	v_lshlrev_b32_e32 v106, 16, v106
	v_mul_f32_e32 v143, v208, v218
	v_rcp_f32_e32 v208, v140
	v_mul_f32_e32 v140, v158, v225
	v_rcp_f32_e32 v158, v114
	v_add_f32_e32 v114, 1.0, v188
	v_add_f32_e32 v184, 1.0, v184
	v_exp_f32_e32 v188, v110
	v_exp_f32_e32 v108, v108
	v_mul_f32_e32 v106, 0xbfb8aa3b, v106
	v_rcp_f32_e32 v110, v184
	v_exp_f32_e32 v184, v106
	v_lshlrev_b32_e32 v105, 16, v105
	v_mul_f32_e32 v132, v132, v224
	v_mul_f32_e32 v105, 0xbfb8aa3b, v105
	v_lshlrev_b32_e32 v104, 16, v104
	v_mul_f32_e32 v109, v196, v225
	v_mul_f32_e32 v196, v132, v231
	v_add_f32_e32 v132, 1.0, v188
	v_add_f32_e32 v108, 1.0, v108
	v_mul_f32_e32 v106, v173, v224
	v_exp_f32_e32 v173, v105
	v_mul_f32_e32 v104, 0xbfb8aa3b, v104
	v_mul_f32_e32 v162, v209, v215
	v_rcp_f32_e32 v209, v132
	v_mul_f32_e32 v132, v155, v224
	v_rcp_f32_e32 v155, v108
	v_add_f32_e32 v108, 1.0, v184
	v_exp_f32_e32 v184, v104
	v_lshlrev_b32_e32 v102, 16, v102
	v_mul_f32_e32 v102, 0xbfb8aa3b, v102
	v_lshlrev_b32_e32 v65, 16, v65
	v_add_f32_e32 v173, 1.0, v173
	v_mul_f32_e32 v125, v125, v220
	v_exp_f32_e32 v102, v102
	v_mul_f32_e32 v65, 0xbfb8aa3b, v65
	v_rcp_f32_e32 v104, v173
	v_mul_f32_e32 v173, v125, v231
	v_add_f32_e32 v125, 1.0, v184
	v_exp_f32_e32 v184, v65
	v_lshlrev_b32_e32 v63, 16, v63
	v_mul_f32_e32 v63, 0xbfb8aa3b, v63
	v_lshlrev_b32_e32 v64, 16, v64
	v_add_f32_e32 v102, 1.0, v102
	v_mul_f32_e32 v65, v164, v220
	v_exp_f32_e32 v164, v63
	v_mul_f32_e32 v64, 0xbfb8aa3b, v64
	v_mul_f32_e32 v149, v210, v216
	v_rcp_f32_e32 v210, v125
	v_mul_f32_e32 v125, v145, v220
	v_rcp_f32_e32 v145, v102
	v_add_f32_e32 v102, 1.0, v184
	v_exp_f32_e32 v184, v64
	v_lshlrev_b32_e32 v62, 16, v62
	v_mul_f32_e32 v62, 0xbfb8aa3b, v62
	v_lshlrev_b32_e32 v60, 16, v60
	v_add_f32_e32 v164, 1.0, v164
	v_exp_f32_e32 v62, v62
	v_mul_f32_e32 v60, 0xbfb8aa3b, v60
	v_rcp_f32_e32 v64, v164
	v_add_f32_e32 v164, 1.0, v184
	v_exp_f32_e32 v184, v60
	v_lshlrev_b32_e32 v59, 16, v59
	v_mul_f32_e32 v59, 0xbfb8aa3b, v59
	v_lshlrev_b32_e32 v57, 16, v57
	v_add_f32_e32 v62, 1.0, v62
	v_mul_f32_e32 v60, v156, v217
	v_exp_f32_e32 v156, v59
	v_mul_f32_e32 v57, 0xbfb8aa3b, v57
	v_mul_f32_e32 v159, v212, v215
	v_rcp_f32_e32 v212, v62
	v_add_f32_e32 v62, 1.0, v184
	v_exp_f32_e32 v184, v57
	v_lshlrev_b32_e32 v52, 16, v52
	v_lshlrev_b32_e32 v55, 16, v55
	v_lshlrev_b32_e32 v53, 16, v53
	v_mul_f32_e32 v52, 0xbfb8aa3b, v52
	v_lshlrev_b32_e32 v50, 16, v50
	s_waitcnt vmcnt(2)
; __device__ __forceinline__ float sigm_(float x) { return __builtin_amdgcn_rcpf(1.0f + __builtin_amdgcn_exp2f(-1.4426950408889634f * x)); }
; __device__ __forceinline__ void attn_unit_pp(int b, int h, int qb, int par, const bf16_t* __restrict__ QBp, const bf16_t* __restrict__ KBp, const bf16_t* __restrict__ VBp, ...
;     ...
;     for (int d0 = 0; d0 < 4; ++d0) sg[d0] = sub_g[d0 * 32 + r32] * 0.8f;
; #pragma unroll
;     for (int r = 0; r < 16; ++r)
; #pragma unroll
;       for (int d0 = 0; d0 < 4; ++d0) { const float ga = __uint_as_float(gate16[r * 4 + d0] << 16); o[d0][r] = o[d0][r] * ss[r] * sg[d0] * sigm_(ga); }
;     __syncthreads();
; #pragma unroll
;     for (int d0 = 0; d0 < 4; ++d0)
; #pragma unroll
;       for (int r = 0; r < 16; ++r) { const int ro = (r & 3) + 8 * (r >> 2);
;         const float val = o[d0][r] + pgs[(d0 * 16 + r) * 64];
;         unsigned u = __float_as_uint(val); u = (u + 0x7fffu + ((u >> 16) & 1u)) >> 16;
;         MIX_ST(ro, d0 * 32, (unsigned short)u); }
	v_mul_f32_e32 v229, 0x3f4ccccd, v235
	v_add_f32_e32 v156, 1.0, v156
	v_mul_f32_e32 v55, 0xbfb8aa3b, v55
	v_mul_f32_e32 v53, 0xbfb8aa3b, v53
	v_exp_f32_e32 v52, v52
	v_mul_f32_e32 v118, v118, v213
	v_mul_f32_e32 v50, 0xbfb8aa3b, v50
	v_rcp_f32_e32 v57, v156
	v_mul_f32_e32 v107, v107, v214
	v_add_f32_e32 v156, 1.0, v184
	v_mul_f32_e32 v127, v127, v214
	v_exp_f32_e32 v184, v55
	v_mul_f32_e32 v55, v146, v214
	v_exp_f32_e32 v146, v53
	v_mul_f32_e32 v53, v170, v214
	v_mul_f32_e32 v214, v118, v229
	v_exp_f32_e32 v118, v50
	v_lshlrev_b32_e32 v49, 16, v49
	v_add_f32_e32 v52, 1.0, v52
	v_mul_f32_e32 v49, 0xbfb8aa3b, v49
	v_lshlrev_b32_e32 v48, 16, v48
	v_rcp_f32_e32 v216, v52
	v_add_f32_e32 v52, 1.0, v118
	v_exp_f32_e32 v118, v49
	v_mul_f32_e32 v48, 0xbfb8aa3b, v48
	v_mul_f32_e32 v50, v136, v213
	v_exp_f32_e32 v136, v48
	v_lshlrev_b32_e32 v47, 16, v47
	v_add_f32_e32 v118, 1.0, v118
	v_mul_f32_e32 v47, 0xbfb8aa3b, v47
	v_lshlrev_b32_e32 v45, 16, v45
	v_rcp_f32_e32 v48, v118
	v_add_f32_e32 v118, 1.0, v136
	v_exp_f32_e32 v47, v47
	v_mul_f32_e32 v45, 0xbfb8aa3b, v45
	v_rcp_f32_e32 v136, v118
	v_exp_f32_e32 v118, v45
	v_lshlrev_b32_e32 v43, 16, v43
	v_add_f32_e32 v47, 1.0, v47
	v_mul_f32_e32 v43, 0xbfb8aa3b, v43
	v_lshlrev_b32_e32 v44, 16, v44
	v_mul_f32_e32 v101, v101, v213
	v_mul_f32_e32 v49, v160, v213
	v_rcp_f32_e32 v213, v47
	v_add_f32_e32 v47, 1.0, v118
	v_exp_f32_e32 v118, v43
	v_mul_f32_e32 v44, 0xbfb8aa3b, v44
	v_mul_f32_e32 v45, v128, v232
	v_exp_f32_e32 v128, v44
	v_add_f32_e32 v118, 1.0, v118
	v_lshlrev_b32_e32 v41, 16, v41
	v_rcp_f32_e32 v44, v118
	v_add_f32_e32 v118, 1.0, v128
	v_mul_f32_e32 v41, 0xbfb8aa3b, v41
	v_lshlrev_b32_e32 v40, 16, v40
	v_rcp_f32_e32 v128, v118
	v_exp_f32_e32 v118, v41
	v_mul_f32_e32 v40, 0xbfb8aa3b, v40
	v_mul_f32_e32 v41, v119, v230
	v_exp_f32_e32 v119, v40
	v_lshlrev_b32_e32 v39, 16, v39
	v_add_f32_e32 v118, 1.0, v118
	v_mul_f32_e32 v39, 0xbfb8aa3b, v39
	v_mul_f32_e32 v43, v153, v232
	v_rcp_f32_e32 v153, v118
	v_add_f32_e32 v118, 1.0, v119
	v_exp_f32_e32 v119, v39
	v_lshlrev_b32_e32 v37, 16, v37
	v_rcp_f32_e32 v39, v118
	v_mul_f32_e32 v37, 0xbfb8aa3b, v37
	v_add_f32_e32 v118, 1.0, v119
	v_lshlrev_b32_e32 v36, 16, v36
	s_waitcnt vmcnt(1)
	v_mul_f32_e32 v228, 0x3f4ccccd, v236
	v_lshlrev_b32_e32 v56, 16, v56
	v_mul_f32_e32 v40, v142, v230
	v_rcp_f32_e32 v142, v118
	v_exp_f32_e32 v37, v37
	v_mul_f32_e32 v112, v112, v226
	v_mul_f32_e32 v36, 0xbfb8aa3b, v36
	s_barrier
	v_and_b32_e32 v5, 63, v174
	v_lshrrev_b32_e32 v6, 5, v5
	v_and_b32_e32 v0, 31, v5
	v_lshlrev_b32_e32 v4, 13, v6
	v_lshl_add_u32 v4, v0, 1, v4
	v_sub_u32_e32 v4, v35, v4
	v_lshrrev_b32_e32 v3, 4, v5
	v_lshl_add_u32 v4, v3, 11, v4
	v_and_b32_e32 v2, 15, v5
	v_lshl_add_u32 v4, v2, 4, v4
	v_lshrrev_b32_e32 v7, 6, v174
	v_lshlrev_b32_e32 v7, 14, v7
	v_add_u32_e32 v7, 0x10800, v7
	v_mul_u32_u24_e32 v3, 272, v3
	v_lshl_add_u32 v3, v2, 4, v3
	v_add_u32_e32 v3, v3, v7
	v_mul_u32_u24_e32 v2, 1088, v6
	v_lshl_add_u32 v2, v0, 1, v2
	v_add_u32_e32 v2, v2, v7
	ds_read2st64_b32 v[118:119], v68 offset1:1
	v_mul_f32_e32 v116, v116, v217
	v_mul_f32_e32 v135, v135, v217
	v_mul_f32_e32 v59, v185, v217
	v_mul_f32_e32 v56, 0xbfb8aa3b, v56
	v_mul_f32_e32 v217, v228, v112
	v_exp_f32_e32 v112, v36
	v_exp_f32_e32 v56, v56
	v_add_f32_e32 v37, 1.0, v37
	v_rcp_f32_e32 v218, v37
	v_add_f32_e32 v37, 1.0, v112
	s_waitcnt lgkmcnt(0)
	v_fma_f32 v112, v211, v198, v118
	v_add_f32_e32 v56, 1.0, v56
	v_bfe_u32 v118, v112, 16, 1
	v_mul_f32_e32 v105, v193, v224
	v_mul_f32_e32 v63, v189, v220
	v_rcp_f32_e32 v215, v56
	v_add_f32_e32 v56, 1.0, v184
	ds_read2st64_b32 v[184:185], v68 offset0:2 offset1:3
	ds_read2st64_b32 v[188:189], v68 offset0:4 offset1:5
	ds_read2st64_b32 v[192:193], v68 offset0:6 offset1:7
	v_add3_u32 v112, v112, v118, s66
	v_fmac_f32_e32 v119, v202, v194
	ds_write_b16_d16_hi v2, v112 offset:0
	v_bfe_u32 v112, v119, 16, 1
	v_add3_u32 v112, v119, v112, s66
	ds_write_b16_d16_hi v2, v112 offset:272
	s_waitcnt lgkmcnt(2)
	v_fma_f32 v112, v207, v199, v184
	v_bfe_u32 v118, v112, 16, 1
	v_add3_u32 v112, v112, v118, s66
	v_fmac_f32_e32 v185, v205, v195
	ds_write_b16_d16_hi v2, v112 offset:544
	v_bfe_u32 v112, v185, 16, 1
	v_add3_u32 v112, v185, v112, s66
	ds_write_b16_d16_hi v2, v112 offset:816
	s_waitcnt lgkmcnt(1)
	v_fma_f32 v112, v201, v191, v188
	v_bfe_u32 v118, v112, 16, 1
	v_add3_u32 v112, v112, v118, s66
	v_fmac_f32_e32 v189, v204, v197
	ds_write_b16_d16_hi v2, v112 offset:2176
	v_bfe_u32 v112, v189, 16, 1
	v_add3_u32 v112, v189, v112, s66
	ds_write_b16_d16_hi v2, v112 offset:2448
	s_waitcnt lgkmcnt(0)
	v_fma_f32 v112, v203, v206, v192
	v_bfe_u32 v118, v112, 16, 1
	v_add3_u32 v112, v112, v118, s66
	ds_write_b16_d16_hi v2, v112 offset:2720
	ds_read2st64_b32 v[118:119], v68 offset0:8 offset1:9
	v_lshlrev_b32_e32 v54, 16, v54
	v_fmac_f32_e32 v193, v208, v200
	v_mul_f32_e32 v54, 0xbfb8aa3b, v54
	v_bfe_u32 v112, v193, 16, 1
	v_exp_f32_e32 v170, v54
	v_mul_f32_e32 v36, v144, v226
	v_add3_u32 v112, v193, v112, s66
	ds_write_b16_d16_hi v2, v112 offset:2992
	s_waitcnt lgkmcnt(0)
	v_fma_f32 v112, v209, v196, v118
	v_rcp_f32_e32 v164, v164
	v_bfe_u32 v118, v112, 16, 1
	v_rcp_f32_e32 v156, v156
	v_add_f32_e32 v146, 1.0, v146
	ds_read2st64_b32 v[184:185], v68 offset0:10 offset1:11
	ds_read2st64_b32 v[188:189], v68 offset0:12 offset1:13
	ds_read2st64_b32 v[192:193], v68 offset0:14 offset1:15
	v_add3_u32 v112, v112, v118, s66
	v_fmac_f32_e32 v119, v210, v173
	v_rcp_f32_e32 v54, v146
	v_add_f32_e32 v146, 1.0, v170
	ds_write_b16_d16_hi v2, v112 offset:4352
	v_bfe_u32 v112, v119, 16, 1
	v_mul_f32_e32 v116, v116, v231
	v_rcp_f32_e32 v146, v146
	v_add3_u32 v112, v119, v112, s66
	v_mul_f32_e32 v107, v107, v231
	ds_write_b16_d16_hi v2, v112 offset:4624
	s_waitcnt lgkmcnt(2)
; __device__ __forceinline__ void attn_unit_pp(int b, int h, int qb, int par, const bf16_t* __restrict__ QBp, const bf16_t* __restrict__ KBp, const bf16_t* __restrict__ VBp, ...
;     ...
; #pragma unroll
;     for (int d0 = 0; d0 < 4; ++d0)
; #pragma unroll
;       for (int r = 0; r < 16; ++r) { const int ro = (r & 3) + 8 * (r >> 2);
;         const float val = o[d0][r] + pgs[(d0 * 16 + r) * 64];
;         unsigned u = __float_as_uint(val); u = (u + 0x7fffu + ((u >> 16) & 1u)) >> 16;
;         MIX_ST(ro, d0 * 32, (unsigned short)u); }
	v_fma_f32 v112, v164, v116, v184
	v_bfe_u32 v116, v112, 16, 1
	v_fmac_f32_e32 v185, v156, v107
	v_mul_f32_e32 v101, v101, v231
	v_mul_f32_e32 v58, v58, v232
	v_add3_u32 v112, v112, v116, s66
	v_bfe_u32 v107, v185, 16, 1
	v_mul_f32_e32 v58, v58, v231
	ds_write_b16_d16_hi v2, v112 offset:4896
	v_add3_u32 v107, v185, v107, s66
	s_waitcnt lgkmcnt(1)
	v_fma_f32 v101, v146, v101, v188
	v_mul_f32_e32 v51, v51, v230
	ds_write_b16_d16_hi v2, v107 offset:5168
	v_bfe_u32 v107, v101, 16, 1
	v_fmac_f32_e32 v189, v136, v58
	v_mul_f32_e32 v51, v51, v231
	v_mul_f32_e32 v46, v46, v226
	v_add3_u32 v101, v101, v107, s66
	v_bfe_u32 v58, v189, 16, 1
	ds_read2st64_b32 v[118:119], v68 offset0:16 offset1:17
	v_mul_f32_e32 v46, v231, v46
	ds_write_b16_d16_hi v2, v101 offset:6528
	v_add3_u32 v58, v189, v58, s66
	s_waitcnt lgkmcnt(1)
	v_fma_f32 v51, v128, v51, v192
	ds_write_b16_d16_hi v2, v58 offset:6800
	v_bfe_u32 v58, v51, 16, 1
	v_fmac_f32_e32 v193, v142, v46
	v_add3_u32 v51, v51, v58, s66
	v_bfe_u32 v46, v193, 16, 1
	v_mul_f32_e32 v165, v165, v229
	ds_write_b16_d16_hi v2, v51 offset:7072
	v_add3_u32 v46, v193, v46, s66
	ds_write_b16_d16_hi v2, v46 offset:7344
	s_waitcnt lgkmcnt(0)
	v_fma_f32 v51, v169, v165, v118
	v_mul_f32_e32 v180, v180, v229
	v_bfe_u32 v58, v51, 16, 1
	ds_read2st64_b32 v[184:185], v68 offset0:18 offset1:19
	ds_read2st64_b32 v[188:189], v68 offset0:20 offset1:21
	ds_read2st64_b32 v[192:193], v68 offset0:22 offset1:23
	v_add3_u32 v51, v51, v58, s66
	v_fmac_f32_e32 v119, v181, v180
	ds_write_b16_d16_hi v2, v51 offset:64
	v_bfe_u32 v46, v119, 16, 1
	v_mul_f32_e32 v182, v182, v229
	v_add3_u32 v46, v119, v46, s66
	ds_write_b16_d16_hi v2, v46 offset:336
	s_waitcnt lgkmcnt(2)
	v_fma_f32 v46, v183, v182, v184
	v_mul_f32_e32 v186, v186, v229
	v_bfe_u32 v51, v46, 16, 1
	v_add3_u32 v46, v46, v51, s66
	v_fmac_f32_e32 v185, v190, v186
	ds_write_b16_d16_hi v2, v46 offset:608
	v_bfe_u32 v46, v185, 16, 1
	v_mul_f32_e32 v171, v171, v229
	v_add3_u32 v46, v185, v46, s66
	ds_write_b16_d16_hi v2, v46 offset:880
	s_waitcnt lgkmcnt(1)
	v_fma_f32 v46, v187, v171, v188
	v_mul_f32_e32 v161, v161, v229
	v_bfe_u32 v51, v46, 16, 1
	v_add3_u32 v46, v46, v51, s66
	v_fmac_f32_e32 v189, v172, v161
	ds_write_b16_d16_hi v2, v46 offset:2240
	v_bfe_u32 v46, v189, 16, 1
	v_mul_f32_e32 v150, v150, v229
	v_add3_u32 v46, v189, v46, s66
	ds_write_b16_d16_hi v2, v46 offset:2512
	s_waitcnt lgkmcnt(0)
	v_fma_f32 v46, v167, v150, v192
	ds_read2st64_b32 v[118:119], v68 offset0:24 offset1:25
	v_mul_f32_e32 v140, v140, v229
	v_bfe_u32 v51, v46, 16, 1
	v_add3_u32 v46, v46, v51, s66
	v_fmac_f32_e32 v193, v158, v140
	ds_write_b16_d16_hi v2, v46 offset:2784
	v_bfe_u32 v46, v193, 16, 1
	v_mul_f32_e32 v132, v132, v229
	v_add3_u32 v46, v193, v46, s66
	ds_write_b16_d16_hi v2, v46 offset:3056
	s_waitcnt lgkmcnt(0)
	v_fma_f32 v46, v155, v132, v118
	v_mul_f32_e32 v125, v125, v229
	v_bfe_u32 v51, v46, 16, 1
	ds_read2st64_b32 v[160:161], v68 offset0:26 offset1:27
	ds_read2st64_b32 v[164:165], v68 offset0:28 offset1:29
	ds_read2st64_b32 v[170:171], v68 offset0:30 offset1:31
	v_add3_u32 v46, v46, v51, s66
	v_fmac_f32_e32 v119, v145, v125
	v_lshlrev_b32_e32 v42, 16, v42
	ds_write_b16_d16_hi v2, v46 offset:4416
	v_bfe_u32 v46, v119, 16, 1
	v_mul_f32_e32 v135, v135, v229
	v_mul_f32_e32 v42, 0xbfb8aa3b, v42
	v_lshlrev_b32_e32 v38, 16, v38
	v_add3_u32 v46, v119, v46, s66
	v_exp_f32_e32 v42, v42
	v_mul_f32_e32 v38, 0xbfb8aa3b, v38
	ds_write_b16_d16_hi v2, v46 offset:4688
	s_waitcnt lgkmcnt(2)
	v_fma_f32 v46, v212, v135, v160
	v_mul_f32_e32 v127, v127, v229
	v_exp_f32_e32 v38, v38
	v_bfe_u32 v51, v46, 16, 1
	v_add3_u32 v46, v46, v51, s66
	v_fmac_f32_e32 v161, v215, v127
	ds_write_b16_d16_hi v2, v46 offset:4960
	v_bfe_u32 v46, v161, 16, 1
	v_add_f32_e32 v42, 1.0, v42
	v_add3_u32 v46, v161, v46, s66
	v_mul_f32_e32 v111, v111, v232
	v_rcp_f32_e32 v42, v42
	v_add_f32_e32 v38, 1.0, v38
	ds_write_b16_d16_hi v2, v46 offset:5232
	s_waitcnt lgkmcnt(1)
	v_fma_f32 v46, v216, v214, v164
	v_mul_f32_e32 v111, v111, v229
	v_rcp_f32_e32 v38, v38
	v_bfe_u32 v51, v46, 16, 1
	v_mul_f32_e32 v103, v103, v230
	v_add3_u32 v46, v46, v51, s66
	v_fmac_f32_e32 v165, v213, v111
	v_mul_f32_e32 v103, v103, v229
	v_mul_f32_e32 v61, v61, v226
	ds_write_b16_d16_hi v2, v46 offset:6592
	v_bfe_u32 v46, v165, 16, 1
	ds_read2st64_b32 v[118:119], v68 offset0:32 offset1:33
	v_rcp_f32_e32 v163, v163
	v_mul_f32_e32 v61, v229, v61
	v_add3_u32 v46, v165, v46, s66
	s_waitcnt lgkmcnt(1)
	v_fma_f32 v42, v42, v103, v170
	ds_write_b16_d16_hi v2, v46 offset:6864
	v_bfe_u32 v46, v42, 16, 1
	v_fmac_f32_e32 v171, v38, v61
	v_rcp_f32_e32 v154, v154
	v_add3_u32 v42, v42, v46, s66
	v_bfe_u32 v38, v171, 16, 1
	v_mul_f32_e32 v162, v162, v228
	ds_write_b16_d16_hi v2, v42 offset:7136
	v_add3_u32 v38, v171, v38, s66
	ds_write_b16_d16_hi v2, v38 offset:7408
	s_waitcnt lgkmcnt(0)
	v_fma_f32 v42, v163, v162, v118
	v_mul_f32_e32 v152, v152, v228
	v_rcp_f32_e32 v148, v148
	v_bfe_u32 v46, v42, 16, 1
	ds_read2st64_b32 v[144:145], v68 offset0:34 offset1:35
	ds_read2st64_b32 v[160:161], v68 offset0:36 offset1:37
	ds_read2st64_b32 v[164:165], v68 offset0:38 offset1:39
	v_add3_u32 v42, v42, v46, s66
	v_fmac_f32_e32 v119, v154, v152
	v_rcp_f32_e32 v139, v139
	ds_write_b16_d16_hi v2, v42 offset:128
	v_bfe_u32 v38, v119, 16, 1
	v_mul_f32_e32 v147, v147, v228
	v_add3_u32 v38, v119, v38, s66
	ds_write_b16_d16_hi v2, v38 offset:400
	s_waitcnt lgkmcnt(2)
	v_fma_f32 v38, v148, v147, v144
	v_mul_f32_e32 v138, v138, v228
	v_rcp_f32_e32 v133, v133
	v_bfe_u32 v42, v38, 16, 1
	v_add3_u32 v38, v38, v42, s66
	v_fmac_f32_e32 v145, v139, v138
	v_rcp_f32_e32 v126, v126
	ds_write_b16_d16_hi v2, v38 offset:672
	v_bfe_u32 v38, v145, 16, 1
	v_mul_f32_e32 v131, v131, v228
	v_add3_u32 v38, v145, v38, s66
	ds_write_b16_d16_hi v2, v38 offset:944
	s_waitcnt lgkmcnt(1)
; __device__ __forceinline__ void attn_unit_pp(int b, int h, int qb, int par, const bf16_t* __restrict__ QBp, const bf16_t* __restrict__ KBp, const bf16_t* __restrict__ VBp, ...
;     ...
; #pragma unroll
;     for (int d0 = 0; d0 < 4; ++d0)
; #pragma unroll
;       for (int r = 0; r < 16; ++r) { const int ro = (r & 3) + 8 * (r >> 2);
;         const float val = o[d0][r] + pgs[(d0 * 16 + r) * 64];
;         unsigned u = __float_as_uint(val); u = (u + 0x7fffu + ((u >> 16) & 1u)) >> 16;
;         MIX_ST(ro, d0 * 32, (unsigned short)u); }
	v_fma_f32 v38, v133, v131, v160
	v_mul_f32_e32 v124, v124, v228
	v_rcp_f32_e32 v121, v121
	v_rcp_f32_e32 v114, v114
	v_bfe_u32 v42, v38, 16, 1
	v_add3_u32 v38, v38, v42, s66
	v_fmac_f32_e32 v161, v126, v124
	ds_write_b16_d16_hi v2, v38 offset:2304
	v_bfe_u32 v38, v161, 16, 1
	v_mul_f32_e32 v120, v120, v228
	v_mul_f32_e32 v113, v113, v228
	v_add3_u32 v38, v161, v38, s66
	ds_write_b16_d16_hi v2, v38 offset:2576
	s_waitcnt lgkmcnt(0)
	v_fma_f32 v38, v121, v120, v164
	v_fmac_f32_e32 v165, v114, v113
	ds_read2st64_b32 v[112:113], v68 offset0:40 offset1:41
	v_rcp_f32_e32 v108, v108
	v_bfe_u32 v42, v38, 16, 1
	v_add3_u32 v38, v38, v42, s66
	v_rcp_f32_e32 v102, v102
	ds_write_b16_d16_hi v2, v38 offset:2848
	v_bfe_u32 v38, v165, 16, 1
	v_mul_f32_e32 v106, v106, v228
	v_add3_u32 v38, v165, v38, s66
	ds_write_b16_d16_hi v2, v38 offset:3120
	s_waitcnt lgkmcnt(0)
	v_fma_f32 v38, v108, v106, v112
	v_mul_f32_e32 v65, v65, v228
	v_rcp_f32_e32 v62, v62
	v_bfe_u32 v42, v38, 16, 1
	ds_read2st64_b32 v[118:119], v68 offset0:42 offset1:43
	ds_read2st64_b32 v[120:121], v68 offset0:44 offset1:45
	ds_read2st64_b32 v[124:125], v68 offset0:46 offset1:47
	v_add3_u32 v38, v38, v42, s66
	v_fmac_f32_e32 v113, v102, v65
	v_rcp_f32_e32 v56, v56
	ds_write_b16_d16_hi v2, v38 offset:4480
	v_bfe_u32 v38, v113, 16, 1
	v_mul_f32_e32 v60, v60, v228
	v_add3_u32 v38, v113, v38, s66
	ds_write_b16_d16_hi v2, v38 offset:4752
	s_waitcnt lgkmcnt(2)
	v_fma_f32 v38, v62, v60, v118
	v_mul_f32_e32 v55, v55, v228
	v_rcp_f32_e32 v52, v52
	v_bfe_u32 v42, v38, 16, 1
	v_add3_u32 v38, v38, v42, s66
	v_fmac_f32_e32 v119, v56, v55
	v_rcp_f32_e32 v47, v47
	ds_write_b16_d16_hi v2, v38 offset:5024
	v_bfe_u32 v38, v119, 16, 1
	v_mul_f32_e32 v50, v50, v228
	v_add3_u32 v38, v119, v38, s66
	ds_write_b16_d16_hi v2, v38 offset:5296
	s_waitcnt lgkmcnt(1)
	v_fma_f32 v38, v52, v50, v120
	v_mul_f32_e32 v45, v45, v228
	v_bfe_u32 v42, v38, 16, 1
	v_add3_u32 v38, v38, v42, s66
	v_fmac_f32_e32 v121, v47, v45
	ds_write_b16_d16_hi v2, v38 offset:6656
	v_bfe_u32 v38, v121, 16, 1
	v_mul_f32_e32 v41, v41, v228
	v_add3_u32 v38, v121, v38, s66
	ds_write_b16_d16_hi v2, v38 offset:6928
	s_waitcnt lgkmcnt(0)
	v_fma_f32 v38, v153, v41, v124
	ds_read2st64_b32 v[46:47], v68 offset0:48 offset1:49
	v_bfe_u32 v41, v38, 16, 1
	v_add3_u32 v38, v38, v41, s66
	v_fmac_f32_e32 v125, v218, v217
	s_waitcnt vmcnt(0)
	v_mul_f32_e32 v227, 0x3f4ccccd, v237
	ds_write_b16_d16_hi v2, v38 offset:7200
	v_bfe_u32 v38, v125, 16, 1
	v_mul_f32_e32 v159, v159, v227
	v_add3_u32 v38, v125, v38, s66
	ds_write_b16_d16_hi v2, v38 offset:7472
	s_waitcnt lgkmcnt(0)
	v_fma_f32 v41, v157, v159, v46
	v_mul_f32_e32 v149, v149, v227
	v_bfe_u32 v42, v41, 16, 1
	ds_read2st64_b32 v[50:51], v68 offset0:50 offset1:51
	ds_read2st64_b32 v[60:61], v68 offset0:52 offset1:53
	ds_read2st64_b32 v[102:103], v68 offset0:54 offset1:55
	v_add3_u32 v41, v41, v42, s66
	v_fmac_f32_e32 v47, v151, v149
	ds_write_b16_d16_hi v2, v41 offset:192
	v_bfe_u32 v38, v47, 16, 1
	v_mul_f32_e32 v143, v143, v227
	v_add3_u32 v38, v47, v38, s66
	ds_write_b16_d16_hi v2, v38 offset:464
	s_waitcnt lgkmcnt(2)
	v_fma_f32 v38, v141, v143, v50
	v_mul_f32_e32 v134, v134, v227
	v_bfe_u32 v41, v38, 16, 1
	v_add3_u32 v38, v38, v41, s66
	v_fmac_f32_e32 v51, v137, v134
	ds_write_b16_d16_hi v2, v38 offset:736
	v_bfe_u32 v38, v51, 16, 1
	v_mul_f32_e32 v130, v130, v227
	v_add3_u32 v38, v51, v38, s66
	ds_write_b16_d16_hi v2, v38 offset:1008
	s_waitcnt lgkmcnt(1)
	v_fma_f32 v38, v129, v130, v60
	v_mul_f32_e32 v122, v122, v227
	v_bfe_u32 v41, v38, 16, 1
	v_add3_u32 v38, v38, v41, s66
	v_fmac_f32_e32 v61, v123, v122
	ds_write_b16_d16_hi v2, v38 offset:2368
	v_bfe_u32 v38, v61, 16, 1
	v_mul_f32_e32 v117, v117, v227
	v_add3_u32 v38, v61, v38, s66
	ds_write_b16_d16_hi v2, v38 offset:2640
	s_waitcnt lgkmcnt(0)
	v_fma_f32 v38, v115, v117, v102
	ds_read2st64_b32 v[46:47], v68 offset0:56 offset1:57
	v_mul_f32_e32 v109, v109, v227
	v_bfe_u32 v41, v38, 16, 1
	v_add3_u32 v38, v38, v41, s66
	v_fmac_f32_e32 v103, v110, v109
	ds_write_b16_d16_hi v2, v38 offset:2912
	v_bfe_u32 v38, v103, 16, 1
	v_mul_f32_e32 v105, v105, v227
	v_add3_u32 v38, v103, v38, s66
	ds_write_b16_d16_hi v2, v38 offset:3184
	s_waitcnt lgkmcnt(0)
	v_fma_f32 v38, v104, v105, v46
	v_mul_f32_e32 v63, v63, v227
	v_bfe_u32 v41, v38, 16, 1
	ds_read2st64_b32 v[50:51], v68 offset0:58 offset1:59
	ds_read2st64_b32 v[60:61], v68 offset0:60 offset1:61
	ds_read2st64_b32 v[102:103], v68 offset0:62 offset1:63
	v_add3_u32 v38, v38, v41, s66
	v_fmac_f32_e32 v47, v64, v63
	ds_write_b16_d16_hi v2, v38 offset:4544
	v_bfe_u32 v38, v47, 16, 1
	v_mul_f32_e32 v59, v59, v227
	v_add3_u32 v38, v47, v38, s66
	ds_write_b16_d16_hi v2, v38 offset:4816
	s_waitcnt lgkmcnt(2)
	v_fma_f32 v38, v57, v59, v50
	v_mul_f32_e32 v53, v53, v227
	v_bfe_u32 v41, v38, 16, 1
	v_add3_u32 v38, v38, v41, s66
	v_fmac_f32_e32 v51, v54, v53
	ds_write_b16_d16_hi v2, v38 offset:5088
	v_bfe_u32 v38, v51, 16, 1
	v_mul_f32_e32 v49, v49, v227
	v_add3_u32 v38, v51, v38, s66
	ds_write_b16_d16_hi v2, v38 offset:5360
	s_waitcnt lgkmcnt(1)
	v_fma_f32 v38, v48, v49, v60
	v_mul_f32_e32 v43, v43, v227
	v_rcp_f32_e32 v37, v37
	v_bfe_u32 v41, v38, 16, 1
	v_add3_u32 v38, v38, v41, s66
	v_fmac_f32_e32 v61, v44, v43
	ds_write_b16_d16_hi v2, v38 offset:6720
	v_bfe_u32 v38, v61, 16, 1
	v_mul_f32_e32 v40, v40, v227
	v_mul_f32_e32 v36, v227, v36
	v_add3_u32 v38, v61, v38, s66
	ds_write_b16_d16_hi v2, v38 offset:6992
	s_waitcnt lgkmcnt(0)
	v_fma_f32 v38, v39, v40, v102
	v_fmac_f32_e32 v103, v37, v36
	v_bfe_u32 v39, v38, 16, 1
	v_bfe_u32 v36, v103, 16, 1
	v_add3_u32 v38, v38, v39, s66
	v_add3_u32 v36, v103, v36, s66
	ds_write_b16_d16_hi v2, v38 offset:7264
	ds_write_b16_d16_hi v2, v36 offset:7536
	s_waitcnt lgkmcnt(0)
	ds_read_b128 v[8:11], v3
	ds_read_b128 v[12:15], v3 offset:1088
	ds_read_b128 v[16:19], v3 offset:2176
	ds_read_b128 v[20:23], v3 offset:3264
	ds_read_b128 v[24:27], v3 offset:4352
	ds_read_b128 v[28:31], v3 offset:5440
	ds_read_b128 v[70:73], v3 offset:6528
	ds_read_b128 v[74:77], v3 offset:7616
	v_add_u32_e32 v5, 0x2000, v4
	v_add_u32_e32 v6, 0x4000, v4
	v_add_u32_e32 v7, 0x6000, v4
	v_add_u32_e32 v0, 0x8000, v4
	v_add_u32_e32 v32, 0xa000, v4
	v_add_u32_e32 v33, 0xc000, v4
	v_add_u32_e32 v34, 0xe000, v4
	s_waitcnt lgkmcnt(7)
	global_store_dwordx4 v4, v[8:11], s[24:25]
	s_waitcnt lgkmcnt(6)
	global_store_dwordx4 v5, v[12:15], s[24:25]
	s_waitcnt lgkmcnt(5)
	global_store_dwordx4 v6, v[16:19], s[24:25]
	s_waitcnt lgkmcnt(4)
	global_store_dwordx4 v7, v[20:23], s[24:25]
	s_waitcnt lgkmcnt(3)
	global_store_dwordx4 v0, v[24:27], s[24:25]
	s_waitcnt lgkmcnt(2)
	global_store_dwordx4 v32, v[28:31], s[24:25]
	s_waitcnt lgkmcnt(1)
	global_store_dwordx4 v33, v[70:73], s[24:25]
	s_waitcnt lgkmcnt(0)
	global_store_dwordx4 v34, v[74:77], s[24:25]
	s_cbranch_execnz .LBB0_338

; __global__ void __launch_bounds__(NWAVES * 64) mega_fwd(Args args) {
	.amdhsa_kernel _Z8mega_fwd4Args
		.amdhsa_group_segment_fixed_size 0
		.amdhsa_private_segment_fixed_size 0
		.amdhsa_kernarg_size 424
		.amdhsa_user_sgpr_count 2
		.amdhsa_user_sgpr_dispatch_ptr 0
		.amdhsa_user_sgpr_queue_ptr 0
		.amdhsa_user_sgpr_kernarg_segment_ptr 1
		.amdhsa_user_sgpr_dispatch_id 0
		.amdhsa_user_sgpr_kernarg_preload_length 0
		.amdhsa_user_sgpr_kernarg_preload_offset 0
		.amdhsa_user_sgpr_private_segment_size 0
		.amdhsa_uses_dynamic_stack 0
		.amdhsa_enable_private_segment 0
		.amdhsa_system_sgpr_workgroup_id_x 1
		.amdhsa_system_sgpr_workgroup_id_y 0
		.amdhsa_system_sgpr_workgroup_id_z 0
		.amdhsa_system_sgpr_workgroup_info 0
		.amdhsa_system_vgpr_workitem_id 2
		.amdhsa_next_free_vgpr 239
		.amdhsa_next_free_sgpr 102
		.amdhsa_accum_offset 240
		.amdhsa_reserve_vcc 1
		.amdhsa_float_round_mode_32 0
		.amdhsa_float_round_mode_16_64 0
		.amdhsa_float_denorm_mode_32 3
		.amdhsa_float_denorm_mode_16_64 3
		.amdhsa_dx10_clamp 1
		.amdhsa_ieee_mode 1
		.amdhsa_fp16_overflow 0
		.amdhsa_tg_split 0
		.amdhsa_exception_fp_ieee_invalid_op 0
		.amdhsa_exception_fp_denorm_src 0
		.amdhsa_exception_fp_ieee_div_zero 0
		.amdhsa_exception_fp_ieee_overflow 0
		.amdhsa_exception_fp_ieee_underflow 0
		.amdhsa_exception_fp_ieee_inexact 0
		.amdhsa_exception_int_div_zero 0
	.end_amdhsa_kernel

; __global__ void __launch_bounds__(NWAVES * 64) mega_fwd(Args args) {
amdhsa.kernels:
  - .agpr_count:     0
    .args:
      - .offset:         0
        .size:           168
        .value_kind:     by_value
      - .offset:         168
        .size:           4
        .value_kind:     hidden_block_count_x
      - .offset:         172
        .size:           4
        .value_kind:     hidden_block_count_y
      - .offset:         176
        .size:           4
        .value_kind:     hidden_block_count_z
      - .offset:         180
        .size:           2
        .value_kind:     hidden_group_size_x
      - .offset:         182
        .size:           2
        .value_kind:     hidden_group_size_y
      - .offset:         184
        .size:           2
        .value_kind:     hidden_group_size_z
      - .offset:         186
        .size:           2
        .value_kind:     hidden_remainder_x
      - .offset:         188
        .size:           2
        .value_kind:     hidden_remainder_y
      - .offset:         190
        .size:           2
        .value_kind:     hidden_remainder_z
      - .offset:         208
        .size:           8
        .value_kind:     hidden_global_offset_x
      - .offset:         216
        .size:           8
        .value_kind:     hidden_global_offset_y
      - .offset:         224
        .size:           8
        .value_kind:     hidden_global_offset_z
      - .offset:         232
        .size:           2
        .value_kind:     hidden_grid_dims
      - .offset:         256
        .size:           8
        .value_kind:     hidden_multigrid_sync_arg
      - .offset:         288
        .size:           4
        .value_kind:     hidden_dynamic_lds_size
    .group_segment_fixed_size: 0
    .kernarg_segment_align: 8
    .kernarg_segment_size: 424
    .language:       OpenCL C
    .language_version:
      - 2
      - 0
    .max_flat_workgroup_size: 512
    .name:           _Z8mega_fwd4Args
    .private_segment_fixed_size: 0
    .sgpr_count:     108
    .sgpr_spill_count: 22
    .symbol:         _Z8mega_fwd4Args.kd
    .uniform_work_group_size: 1
    .uses_dynamic_stack: false
    .vgpr_count:     239
    .vgpr_spill_count: 0
    .wavefront_size: 64
